# attention: hand-scheduled non-diagonal step body, Q fragments kept in registers, plain f32 row sums, setprio 1 on MFMA blocks
# speedup vs baseline: 1.0132x; 1.0061x over previous
; #define LAS __attribute__((address_space(3)))
; #define MFMA32(a, b, c) __builtin_amdgcn_mfma_f32_32x32x16_bf16((a), (b), (c), 0, 0, 0)
; #define ATT_LOADG(t) do { kA = *(const u32x4*)(Kh + (size_t)(t) * 6144 + tid * 8); if (tid < 256) kB = *(const u32x4*)(Kh + (size_t)(t) * 6144 + c2 * 8); \
;         vA = *(const u32x4*)(Vh + (size_t)vr * T + 64 * (t) + vc * 8); } while (0)
; #define ATT_STORE(buf) do { *(LAS u32x4*)(Kb + (buf) * 6656 + kr1 * 104 + kc1 * 8) = kA; if (tid < 256) *(LAS u32x4*)(Kb + (buf) * 6656 + kr2 * 104 + kc2 * 8) = kB; \
;         *(LAS u32x2*)(Vb + (buf) * 4352 + vr * 68 + vc * 8) = (u32x2){vA[0], vA[1]}; *(LAS u32x2*)(Vb + (buf) * 4352 + vr * 68 + vc * 8 + 4) = (u32x2){vA[2], vA[3]}; } while (0)
; #define ATT_LOADG(t) do { kA = *(const u32x4*)(Kh + (size_t)(t) * 6144 + tid * 8); if (tid < 256) kB = *(const u32x4*)(Kh + (size_t)(t) * 6144 + c2 * 8); \
;         vA = *(const u32x4*)(Vh + (size_t)vr * T + 64 * (t) + vc * 8); } while (0)
; #define ATT_STORE(buf) do { *(LAS u32x4*)(Kb + (buf) * 6656 + kr1 * 104 + kc1 * 8) = kA; if (tid < 256) *(LAS u32x4*)(Kb + (buf) * 6656 + kr2 * 104 + kc2 * 8) = kB; \
;         *(LAS u32x2*)(Vb + (buf) * 4352 + vr * 68 + vc * 8) = (u32x2){vA[0], vA[1]}; *(LAS u32x2*)(Vb + (buf) * 4352 + vr * 68 + vc * 8 + 4) = (u32x2){vA[2], vA[3]}; } while (0)
; __device__ __forceinline__ void attn_unit64(const bf16_t* Q, const bf16_t* K, const bf16_t* Vt, bf16_t* O, int bh, int qb8, float mfix, LAS unsigned char* lds) {
;     ...
; #pragma unroll
;     for (int i = 0; i < 16; ++i) { oA0[i] = 0.f; oA1[i] = 0.f; oB0[i] = 0.f; oB1[i] = 0.f; }
;     float lA = 0.f, lB = 0.f;
;     const int c2 = 512 + tid, kr1 = tid / 12, kc1 = tid % 12, kr2 = c2 / 12, kc2 = c2 % 12, vr = tid >> 3, vc = tid & 7;
;     u32x4 kA, kB = {0u, 0u, 0u, 0u}, vA;
;     ...
;     ATT_LOADG(0); ATT_STORE(0); __syncthreads();
;     ...
;                 for (int d0 = 0; d0 < 6; ++d0) { const bf16x8 a = *(const LAS bf16x8*)(kp + half * 32 * 104 + 16 * d0); const bf16x8 qa_ = Qs[512 * d0], qb_ = Qs[512 * (6 + d0)]; sA = MFMA32(a, qa_, sA); sB = MFMA32(a, qb_, sB); }
.LBB0_790:
	s_or_b64 exec, exec, s[4:5]
	global_load_dwordx4 v[120:123], v[150:151], off
	s_waitcnt vmcnt(1)
	ds_write_b128 v197, v[112:115]
	s_and_saveexec_b64 s[4:5], s[0:1]
	v_add_u32_e32 v16, v196, v190
	ds_write_b128 v16, v[116:119]
	s_or_b64 exec, exec, s[4:5]
	s_lshl_b32 s25, s43, 3
	s_lshr_b32 s24, s16, 6
	s_add_i32 s24, s24, s25
	s_add_i32 s25, s25, 8
	s_add_u32 s4, s50, s58
	v_add_u32_e32 v16, 0x6800, v189
	v_mov_b32_e32 v157, 0
	s_addc_u32 s5, s51, s57
	s_waitcnt vmcnt(0)
	ds_write2_b64 v16, v[120:121], v[122:123] offset1:1
	v_lshl_add_u64 v[16:17], s[4:5], 0, v[156:157]
	s_mov_b64 s[4:5], 0x4003000
	v_lshl_add_u64 v[124:125], v[16:17], 0, s[4:5]
	s_lshl_b32 s4, s2, 20
	s_and_b32 s4, s4, 0x1c00000
	v_lshlrev_b32_e32 v16, 13, v254
	s_add_u32 s4, s8, s4
	v_and_b32_e32 v156, 0x7f0000, v16
	s_addc_u32 s5, s9, 0
	v_and_b32_e32 v18, 7, v254
	v_lshl_add_u64 v[16:17], s[4:5], 0, v[156:157]
	v_lshlrev_b32_e32 v156, 4, v18
	v_lshl_add_u64 v[16:17], v[16:17], 0, v[156:157]
	v_lshl_add_u64 v[16:17], s[30:31], 0, v[16:17]
	s_mov_b64 s[4:5], 0x10000080
	v_mov_b32_e32 v64, v157
	v_mov_b32_e32 v65, v157
	v_lshl_add_u64 v[126:127], v[16:17], 0, s[4:5]
	v_mov_b32_e32 v66, v157
	v_mov_b32_e32 v67, v157
	v_mov_b32_e32 v68, v157
	v_mov_b32_e32 v69, v157
	v_mov_b32_e32 v70, v157
	v_mov_b32_e32 v71, v157
	v_mov_b32_e32 v72, v157
	v_mov_b32_e32 v73, v157
	v_mov_b32_e32 v74, v157
	v_mov_b32_e32 v75, v157
	v_mov_b32_e32 v76, v157
	v_mov_b32_e32 v77, v157
	v_mov_b32_e32 v78, v157
	v_mov_b32_e32 v79, v157
	v_mov_b64_e32 v[48:49], v[64:65]
	v_mov_b64_e32 v[32:33], v[64:65]
	v_mov_b64_e32 v[16:17], v[64:65]
	s_addk_i32 s26, 0x200
	s_mov_b32 s27, 0
	v_mov_b32_e32 v156, v157
	s_mov_b64 s[16:17], 0x3000
	s_mov_b64 s[18:19], 0x80
	v_mov_b32_e32 v176, 0xf149f2ca
	v_mov_b64_e32 v[128:129], v[126:127]
	v_mov_b64_e32 v[130:131], v[124:125]
	v_mov_b64_e32 v[50:51], v[66:67]
	v_mov_b64_e32 v[52:53], v[68:69]
	v_mov_b64_e32 v[54:55], v[70:71]
	v_mov_b64_e32 v[56:57], v[72:73]
	v_mov_b64_e32 v[58:59], v[74:75]
	v_mov_b64_e32 v[60:61], v[76:77]
	v_mov_b64_e32 v[62:63], v[78:79]
	v_mov_b64_e32 v[34:35], v[66:67]
	v_mov_b64_e32 v[36:37], v[68:69]
	v_mov_b64_e32 v[38:39], v[70:71]
	v_mov_b64_e32 v[40:41], v[72:73]
	v_mov_b64_e32 v[42:43], v[74:75]
	v_mov_b64_e32 v[44:45], v[76:77]
	v_mov_b64_e32 v[46:47], v[78:79]
	v_mov_b64_e32 v[18:19], v[66:67]
	v_mov_b64_e32 v[20:21], v[68:69]
	v_mov_b64_e32 v[22:23], v[70:71]
	v_mov_b64_e32 v[24:25], v[72:73]
	v_mov_b64_e32 v[26:27], v[74:75]
	v_mov_b64_e32 v[28:29], v[76:77]
	v_mov_b64_e32 v[30:31], v[78:79]
	s_mov_b32 s33, 0
	s_waitcnt lgkmcnt(0)
	s_barrier
	ds_read_b128 v[132:135], v200 offset:44032
	ds_read_b128 v[136:139], v200 offset:52224
	ds_read_b128 v[140:143], v200 offset:60416
	ds_read_b128 v[144:147], v201 offset:24576
	ds_read_b128 v[206:209], v201 offset:32768
	ds_read_b128 v[210:213], v201 offset:40960
	ds_read_b128 v[214:217], v201 offset:49152
	ds_read_b128 v[218:221], v201 offset:57344
	ds_read_b128 v[232:235], v202
	ds_read_b128 v[236:239], v203
	ds_read_b128 v[240:243], v204
	ds_read_b128 v[244:247], v205
	s_waitcnt lgkmcnt(0)

; #define LAS __attribute__((address_space(3)))
; #define MFMA32(a, b, c) __builtin_amdgcn_mfma_f32_32x32x16_bf16((a), (b), (c), 0, 0, 0)
; __device__ __forceinline__ int crow(int r, int hi) { return (r & 3) + 8 * (r >> 2) + 4 * hi; }
; __device__ __forceinline__ void attn_unit64(const bf16_t* Q, const bf16_t* K, const bf16_t* Vt, bf16_t* O, int bh, int qb8, float mfix, LAS unsigned char* lds) {
;     ...
;         if (t <= tmaxw) {
;             const LAS bf16_t* kp = Kb + buf * 6656 + r * 104 + 8 * hh;
;             const LAS bf16_t* vp = Vb + buf * 4352 + r * 68 + 4 * hh;
; #pragma unroll
;             for (int half = 0; half < 2; ++half) {
;                 f32x16 sA, sB;
; #pragma unroll
;                 for (int i = 0; i < 16; ++i) { sA[i] = -mfix; sB[i] = -mfix; }
; #pragma unroll
;                 for (int d0 = 0; d0 < 6; ++d0) { const bf16x8 a = *(const LAS bf16x8*)(kp + half * 32 * 104 + 16 * d0); const bf16x8 qa_ = Qs[512 * d0], qb_ = Qs[512 * (6 + d0)]; sA = MFMA32(a, qa_, sA); sB = MFMA32(a, qb_, sB); }
;                 if (t == tmaxw) {
;                     const int rowA = qw + r, rowB = qw + 32 + r;
; #pragma unroll
;                     for (int i = 0; i < 16; ++i) { const int kv = 64 * t + 32 * half + crow(i, hh); if (kv > rowA) sA[i] = -1e30f; if (kv > rowB) sB[i] = -1e30f; }
;                 }
.LBB0_799:
	s_cmp_lt_u32 s33, s24
	s_cbranch_scc1 .Lattn_fast_1
	s_mul_i32 s4, s29, 0x3400
	v_add_u32_e32 v180, s4, v188
	ds_read_b128 v[132:135], v180
	ds_read_b128 v[80:83], v200 offset:44032
	ds_read_b128 v[136:139], v200 offset:52224
	ds_read_b128 v[140:143], v180 offset:32
	ds_read_b128 v[144:147], v201 offset:49152
	ds_read_b128 v[158:161], v201 offset:40960
	s_cmp_eq_u32 s24, s33
	s_waitcnt lgkmcnt(4)
	v_mfma_f32_32x32x16_bf16 v[96:111], v[132:135], v[80:83], v[0:15]
	v_add_u32_e32 v179, s27, v194
	s_cselect_b64 s[22:23], -1, 0
	s_cmp_lg_u32 s24, s33
	v_cmp_le_i32_e32 vcc, v179, v174
	s_waitcnt lgkmcnt(1)
	v_mfma_f32_32x32x16_bf16 v[80:95], v[132:135], v[144:147], v[0:15]
	v_mfma_f32_32x32x16_bf16 v[96:111], v[140:143], v[136:139], v[96:111]
	ds_read_b128 v[132:135], v201 offset:57344
	ds_read_b128 v[136:139], v201 offset:24576
	s_waitcnt lgkmcnt(1)
	v_mfma_f32_32x32x16_bf16 v[80:95], v[140:143], v[132:135], v[80:95]
	ds_read_b128 v[132:135], v180 offset:64
	ds_read_b128 v[140:143], v200 offset:60416
	ds_read_b128 v[144:147], v180 offset:96
	ds_read_b128 v[162:165], v201 offset:32768
	s_waitcnt lgkmcnt(2)
	v_mfma_f32_32x32x16_bf16 v[96:111], v[132:135], v[140:143], v[96:111]
	ds_read_b128 v[140:143], v202
	ds_read_b128 v[166:169], v203
	s_waitcnt lgkmcnt(1)
	v_mfma_f32_32x32x16_bf16 v[80:95], v[132:135], v[140:143], v[80:95]
	v_mfma_f32_32x32x16_bf16 v[96:111], v[144:147], v[136:139], v[96:111]
	ds_read_b128 v[132:135], v180 offset:128
	ds_read_b128 v[136:139], v180 offset:160
	s_waitcnt lgkmcnt(2)
	v_mfma_f32_32x32x16_bf16 v[80:95], v[144:147], v[166:169], v[80:95]
	ds_read_b128 v[140:143], v204
	ds_read_b128 v[144:147], v205
	s_waitcnt lgkmcnt(3)
	v_mfma_f32_32x32x16_bf16 v[96:111], v[132:135], v[162:165], v[96:111]
	s_waitcnt lgkmcnt(1)
	v_mfma_f32_32x32x16_bf16 v[80:95], v[132:135], v[140:143], v[80:95]
	v_mfma_f32_32x32x16_bf16 v[96:111], v[136:139], v[158:161], v[96:111]
	s_waitcnt lgkmcnt(0)
	v_mfma_f32_32x32x16_bf16 v[80:95], v[136:139], v[144:147], v[80:95]
	s_cbranch_scc1 .LBB0_801
	s_nop 8
	v_cndmask_b32_e32 v96, v176, v96, vcc
	v_cmp_lt_i32_e32 vcc, v179, v175
	v_add_u32_e32 v132, 2, v179
	v_cmp_lt_i32_e64 s[4:5], v179, v174
	v_cndmask_b32_e32 v81, v176, v81, vcc
	v_cmp_le_i32_e32 vcc, v179, v175
	v_cndmask_b32_e64 v97, v176, v97, s[4:5]
	s_nop 0
	v_cndmask_b32_e32 v80, v176, v80, vcc
	v_cmp_le_i32_e32 vcc, v132, v174
	s_nop 1
	v_cndmask_b32_e32 v98, v176, v98, vcc
	v_cmp_le_i32_e32 vcc, v132, v175
	v_add_u32_e32 v132, 3, v179
	s_nop 0
	v_cndmask_b32_e32 v82, v176, v82, vcc
	v_cmp_le_i32_e32 vcc, v132, v174
	s_nop 1
	v_cndmask_b32_e32 v99, v176, v99, vcc
	v_cmp_le_i32_e32 vcc, v132, v175
	v_add_u32_e32 v132, 8, v179
	s_nop 0
	v_cndmask_b32_e32 v83, v176, v83, vcc
	v_cmp_le_i32_e32 vcc, v132, v174
	s_nop 1
	v_cndmask_b32_e32 v100, v176, v100, vcc
	v_cmp_le_i32_e32 vcc, v132, v175
	v_add_u32_e32 v132, 9, v179
	s_nop 0
	v_cndmask_b32_e32 v84, v176, v84, vcc
	v_cmp_le_i32_e32 vcc, v132, v174
	s_nop 1
	v_cndmask_b32_e32 v101, v176, v101, vcc
	v_cmp_le_i32_e32 vcc, v132, v175
	v_add_u32_e32 v132, 10, v179
	s_nop 0
	v_cndmask_b32_e32 v85, v176, v85, vcc
	v_cmp_le_i32_e32 vcc, v132, v174
	s_nop 1
	v_cndmask_b32_e32 v102, v176, v102, vcc
	v_cmp_le_i32_e32 vcc, v132, v175
	v_add_u32_e32 v132, 11, v179
	s_nop 0
	v_cndmask_b32_e32 v86, v176, v86, vcc
	v_cmp_le_i32_e32 vcc, v132, v174
	s_nop 1
	v_cndmask_b32_e32 v103, v176, v103, vcc
	v_cmp_le_i32_e32 vcc, v132, v175
	v_add_u32_e32 v132, 16, v179
	s_nop 0
	v_cndmask_b32_e32 v87, v176, v87, vcc
	v_cmp_le_i32_e32 vcc, v132, v174
	s_nop 1
	v_cndmask_b32_e32 v104, v176, v104, vcc
	v_cmp_le_i32_e32 vcc, v132, v175
	v_add_u32_e32 v132, 17, v179
	s_nop 0
	v_cndmask_b32_e32 v88, v176, v88, vcc
	v_cmp_le_i32_e32 vcc, v132, v174
	s_nop 1
	v_cndmask_b32_e32 v105, v176, v105, vcc
	v_cmp_le_i32_e32 vcc, v132, v175
	v_add_u32_e32 v132, 18, v179
	s_nop 0
	v_cndmask_b32_e32 v89, v176, v89, vcc
	v_cmp_le_i32_e32 vcc, v132, v174
	s_nop 1
	v_cndmask_b32_e32 v106, v176, v106, vcc
	v_cmp_le_i32_e32 vcc, v132, v175
	v_add_u32_e32 v132, 19, v179
	s_nop 0
	v_cndmask_b32_e32 v90, v176, v90, vcc
	v_cmp_le_i32_e32 vcc, v132, v174
	s_nop 1
	v_cndmask_b32_e32 v107, v176, v107, vcc
	v_cmp_le_i32_e32 vcc, v132, v175
	v_add_u32_e32 v132, 24, v179
	s_nop 0
	v_cndmask_b32_e32 v91, v176, v91, vcc
	v_cmp_le_i32_e32 vcc, v132, v174
	s_nop 1
	v_cndmask_b32_e32 v108, v176, v108, vcc
	v_cmp_le_i32_e32 vcc, v132, v175
	v_add_u32_e32 v132, 25, v179
	s_nop 0
	v_cndmask_b32_e32 v92, v176, v92, vcc
	v_cmp_le_i32_e32 vcc, v132, v174
	s_nop 1
	v_cndmask_b32_e32 v109, v176, v109, vcc
	v_cmp_le_i32_e32 vcc, v132, v175
	v_add_u32_e32 v132, 26, v179
	s_nop 0
	v_cndmask_b32_e32 v93, v176, v93, vcc
	v_cmp_le_i32_e32 vcc, v132, v174
	s_nop 1
	v_cndmask_b32_e32 v110, v176, v110, vcc
	v_cmp_le_i32_e32 vcc, v132, v175
	v_add_u32_e32 v132, 27, v179
	s_nop 0
	v_cndmask_b32_e32 v94, v176, v94, vcc
	v_cmp_le_i32_e32 vcc, v132, v174
	s_nop 1
	v_cndmask_b32_e32 v111, v176, v111, vcc
	v_cmp_le_i32_e32 vcc, v132, v175
	s_nop 1
	v_cndmask_b32_e32 v95, v176, v95, vcc

; #define LAS __attribute__((address_space(3)))
; __device__ __forceinline__ unsigned pk2(float lo, float hi) { f32x2_t v = {lo, hi}; bf16x2_t b = __builtin_convertvector(v, bf16x2_t); return __builtin_bit_cast(unsigned, b); }
; #define MFMA32(a, b, c) __builtin_amdgcn_mfma_f32_32x32x16_bf16((a), (b), (c), 0, 0, 0)
; #define ATT_STORE(buf) do { *(LAS u32x4*)(Kb + (buf) * 6656 + kr1 * 104 + kc1 * 8) = kA; if (tid < 256) *(LAS u32x4*)(Kb + (buf) * 6656 + kr2 * 104 + kc2 * 8) = kB; \
;         *(LAS u32x2*)(Vb + (buf) * 4352 + vr * 68 + vc * 8) = (u32x2){vA[0], vA[1]}; *(LAS u32x2*)(Vb + (buf) * 4352 + vr * 68 + vc * 8 + 4) = (u32x2){vA[2], vA[3]}; } while (0)
; __device__ __forceinline__ void attn_unit64(const bf16_t* Q, const bf16_t* K, const bf16_t* Vt, bf16_t* O, int bh, int qb8, float mfix, LAS unsigned char* lds) {
;     ...
;                 float la = 0.f, lb_ = 0.f;
; #pragma unroll
;                 for (int i = 0; i < 16; ++i) { sA[i] = __builtin_amdgcn_exp2f(sA[i]); sB[i] = __builtin_amdgcn_exp2f(sB[i]); la += sA[i]; lb_ += sB[i]; }
;                 lA += la; lB += lb_;
;                 u32x4 pwA[2], pwB[2];
; #pragma unroll
;                 for (int e = 0; e < 4; ++e) { pwA[0][e] = pk2(sA[2 * e], sA[2 * e + 1]); pwA[1][e] = pk2(sA[8 + 2 * e], sA[8 + 2 * e + 1]); pwB[0][e] = pk2(sB[2 * e], sB[2 * e + 1]); pwB[1][e] = pk2(sB[8 + 2 * e], sB[8 + 2 * e + 1]); }
; #pragma unroll
;                 for (int k2 = 0; k2 < 2; ++k2) { const int ks = 2 * half + k2;
;                     const u32x2 va0 = *(const LAS u32x2*)(vp + 16 * ks), va1 = *(const LAS u32x2*)(vp + 16 * ks + 8), vb0 = *(const LAS u32x2*)(vp + 32 * 68 + 16 * ks), vb1 = *(const LAS u32x2*)(vp + 32 * 68 + 16 * ks + 8);
;                     const bf16x8 v0 = __builtin_bit_cast(bf16x8, (u32x4){va0[0], va0[1], va1[0], va1[1]}), v1 = __builtin_bit_cast(bf16x8, (u32x4){vb0[0], vb0[1], vb1[0], vb1[1]});
;                     const bf16x8 pfA = __builtin_bit_cast(bf16x8, pwA[k2]), pfB = __builtin_bit_cast(bf16x8, pwB[k2]);
;                     oA0 = MFMA32(v0, pfA, oA0); oA1 = MFMA32(v1, pfA, oA1); oB0 = MFMA32(v0, pfB, oB0); oB1 = MFMA32(v1, pfB, oB1); }
;                 __builtin_amdgcn_sched_barrier(0);
;             }
;         }
;         if (t + 1 < NTL) ATT_STORE(buf ^ 1);
.LBB0_803:
	v_pk_add_f32 v[132:133], v[132:133], 0 op_sel_hi:[1,0]
	s_nop 7
	v_exp_f32_e32 v93, v93
	v_pk_add_f32 v[132:133], v[134:135], v[132:133]
	v_exp_f32_e32 v135, v80
	v_pk_add_f32 v[132:133], v[136:137], v[132:133]
	v_exp_f32_e32 v134, v96
	v_pk_add_f32 v[132:133], v[138:139], v[132:133]
	v_exp_f32_e32 v137, v81
	v_pk_add_f32 v[132:133], v[140:141], v[132:133]
	v_exp_f32_e32 v136, v97
	v_pk_add_f32 v[132:133], v[146:147], v[132:133]
	v_exp_f32_e32 v139, v82
	v_pk_add_f32 v[132:133], v[144:145], v[132:133]
	v_exp_f32_e32 v138, v98
	v_pk_add_f32 v[132:133], v[142:143], v[132:133]
	v_exp_f32_e32 v141, v83
	v_pk_add_f32 v[132:133], v[162:163], v[132:133]
	v_exp_f32_e32 v140, v99
	v_pk_add_f32 v[132:133], v[166:167], v[132:133]
	ds_read2_b64 v[80:83], v177 offset0:8 offset1:10
	v_pk_add_f32 v[132:133], v[160:161], v[132:133]
	ds_read2_b64 v[96:99], v178 offset0:40 offset1:42
	v_pk_add_f32 v[132:133], v[164:165], v[132:133]
	v_exp_f32_e32 v143, v84
	v_pk_add_f32 v[132:133], v[158:159], v[132:133]
	v_exp_f32_e32 v145, v85
	v_pk_add_f32 v[132:133], v[172:173], v[132:133]
	v_exp_f32_e32 v147, v86
	v_pk_add_f32 v[132:133], v[168:169], v[132:133]
	v_exp_f32_e32 v142, v100
	v_pk_add_f32 v[132:133], v[170:171], v[132:133]
	v_exp_f32_e32 v144, v101
	v_pk_add_f32 v[132:133], v[156:157], v[132:133]
	v_exp_f32_e32 v157, v87
	v_exp_f32_e32 v146, v102
	v_exp_f32_e32 v156, v103
	v_cvt_pk_bf16_f32 v84, v135, v137
	v_cvt_pk_bf16_f32 v85, v139, v141
	v_cvt_pk_bf16_f32 v86, v143, v145
	v_cvt_pk_bf16_f32 v87, v147, v157
	v_exp_f32_e32 v101, v88
	v_exp_f32_e32 v103, v89
	s_waitcnt lgkmcnt(1)
	v_mfma_f32_32x32x16_bf16 v[64:79], v[80:83], v[84:87], v[64:79]
	v_exp_f32_e32 v102, v105
	v_exp_f32_e32 v105, v90
	v_exp_f32_e32 v159, v91
	ds_read2_b64 v[88:91], v178 offset0:44 offset1:46
	v_exp_f32_e32 v158, v107
	v_exp_f32_e32 v107, v92
	v_exp_f32_e32 v92, v109
	s_waitcnt lgkmcnt(1)
	v_mfma_f32_32x32x16_bf16 v[48:63], v[96:99], v[84:87], v[48:63]
	v_cvt_pk_bf16_f32 v84, v134, v136
	v_cvt_pk_bf16_f32 v85, v138, v140
	v_cvt_pk_bf16_f32 v86, v142, v144
	v_cvt_pk_bf16_f32 v87, v146, v156
	v_exp_f32_e32 v109, v94
	v_exp_f32_e32 v95, v95
	v_exp_f32_e32 v100, v104
	v_mfma_f32_32x32x16_bf16 v[32:47], v[80:83], v[84:87], v[32:47]
	ds_read2_b64 v[80:83], v177 offset0:12 offset1:14
	v_exp_f32_e32 v104, v106
	v_exp_f32_e32 v106, v108
	v_exp_f32_e32 v108, v110
	v_exp_f32_e32 v94, v111
	v_mfma_f32_32x32x16_bf16 v[16:31], v[96:99], v[84:87], v[16:31]
	v_add_f32_e64 v96, v134, 0
	v_add_f32_e64 v97, v135, 0
	v_cvt_pk_bf16_f32 v84, v101, v103
	v_add_f32_e64 v96, v136, v96
	v_add_f32_e64 v97, v137, v97
	v_cvt_pk_bf16_f32 v85, v105, v159
	v_pk_add_f32 v[96:97], v[138:139], v[96:97]
	v_cvt_pk_bf16_f32 v86, v107, v93
	v_pk_add_f32 v[96:97], v[140:141], v[96:97]
	v_cvt_pk_bf16_f32 v87, v109, v95
	v_pk_add_f32 v[96:97], v[142:143], v[96:97]
	s_nop 0
	v_pk_add_f32 v[96:97], v[144:145], v[96:97]
	s_waitcnt lgkmcnt(0)
	v_mfma_f32_32x32x16_bf16 v[64:79], v[80:83], v[84:87], v[64:79]
	v_mfma_f32_32x32x16_bf16 v[48:63], v[88:91], v[84:87], v[48:63]
	v_add_f32_e64 v84, v146, v96
	v_add_f32_e64 v85, v147, v97
	v_cvt_pk_bf16_f32 v86, v106, v92
	v_add_f32_e64 v84, v156, v84
	v_add_f32_e64 v85, v157, v85
	v_cvt_pk_bf16_f32 v87, v108, v94
	v_pk_add_f32 v[96:97], v[100:101], v[84:85]
	v_cvt_pk_bf16_f32 v84, v100, v102
	v_cvt_pk_bf16_f32 v85, v104, v158
	s_nop 1
	v_mfma_f32_32x32x16_bf16 v[32:47], v[80:83], v[84:87], v[32:47]
	v_add_f32_e64 v80, v102, v96
	v_add_f32_e64 v81, v103, v97
	v_add_f32_e64 v80, v104, v80
	v_add_f32_e64 v81, v105, v81
	v_add_f32_e64 v80, v158, v80
	v_add_f32_e64 v81, v159, v81
	v_pk_add_f32 v[80:81], v[106:107], v[80:81]
	v_mfma_f32_32x32x16_bf16 v[16:31], v[88:91], v[84:87], v[16:31]
	v_add_f32_e64 v80, v92, v80
	v_add_f32_e64 v81, v93, v81
	v_add_f32_e64 v80, v108, v80
	v_add_f32_e64 v81, v109, v81
	v_add_f32_e64 v80, v94, v80
	v_add_f32_e64 v81, v95, v81
	v_pk_add_f32 v[156:157], v[132:133], v[80:81]
.Lattn_join_1:
	s_andn2_b64 vcc, exec, s[20:21]
	s_cbranch_vccnz .LBB0_807
.LBB0_804:
	s_xor_b32 s20, s29, 1
	s_mul_i32 s4, s20, 0x3400
	s_add_i32 s21, s4, 0
	v_add3_u32 v80, s21, v193, v192
	s_waitcnt vmcnt(1)
	ds_write_b128 v80, v[112:115]
	s_and_saveexec_b64 s[4:5], s[0:1]
	v_add3_u32 v80, s21, v191, v190
	ds_write_b128 v80, v[116:119]
	s_or_b64 exec, exec, s[4:5]
	s_mulk_i32 s20, 0x2200
	v_add_u32_e32 v80, s20, v189
	v_add_u32_e32 v80, 0x6800, v80
	s_waitcnt vmcnt(0)
	ds_write2_b64 v80, v[120:121], v[122:123] offset1:1

; #define LAS __attribute__((address_space(3)))
; __device__ __forceinline__ void attn_unit64(const bf16_t* Q, const bf16_t* K, const bf16_t* Vt, bf16_t* O, int bh, int qb8, float mfix, LAS unsigned char* lds) {
;     ...
;         if (t <= tmaxw) {
;             const LAS bf16_t* kp = Kb + buf * 6656 + r * 104 + 8 * hh;
;             const LAS bf16_t* vp = Vb + buf * 4352 + r * 68 + 4 * hh;
; #pragma unroll
;             for (int half = 0; half < 2; ++half) {
;                 f32x16 sA, sB;
; #pragma unroll
;                 for (int i = 0; i < 16; ++i) { sA[i] = -mfix; sB[i] = -mfix; }
; #pragma unroll
;                 for (int d0 = 0; d0 < 6; ++d0) { const bf16x8 a = *(const LAS bf16x8*)(kp + half * 32 * 104 + 16 * d0); const bf16x8 qa_ = Qs[512 * d0], qb_ = Qs[512 * (6 + d0)]; sA = MFMA32(a, qa_, sA); sB = MFMA32(a, qb_, sB); }
;                 if (t == tmaxw) {
;                     const int rowA = qw + r, rowB = qw + 32 + r;
; #pragma unroll
;                     for (int i = 0; i < 16; ++i) { const int kv = 64 * t + 32 * half + crow(i, hh); if (kv > rowA) sA[i] = -1e30f; if (kv > rowB) sB[i] = -1e30f; }
;                 }
;                 float la = 0.f, lb_ = 0.f;
; #pragma unroll
;                 for (int i = 0; i < 16; ++i) { sA[i] = __builtin_amdgcn_exp2f(sA[i]); sB[i] = __builtin_amdgcn_exp2f(sB[i]); la += sA[i]; lb_ += sB[i]; }
;                 lA += la; lB += lb_;
;                 u32x4 pwA[2], pwB[2];
; #pragma unroll
;                 for (int e = 0; e < 4; ++e) { pwA[0][e] = pk2(sA[2 * e], sA[2 * e + 1]); pwA[1][e] = pk2(sA[8 + 2 * e], sA[8 + 2 * e + 1]); pwB[0][e] = pk2(sB[2 * e], sB[2 * e + 1]); pwB[1][e] = pk2(sB[8 + 2 * e], sB[8 + 2 * e + 1]); }
; #pragma unroll
;                 for (int k2 = 0; k2 < 2; ++k2) { const int ks = 2 * half + k2;
;                     const u32x2 va0 = *(const LAS u32x2*)(vp + 16 * ks), va1 = *(const LAS u32x2*)(vp + 16 * ks + 8), vb0 = *(const LAS u32x2*)(vp + 32 * 68 + 16 * ks), vb1 = *(const LAS u32x2*)(vp + 32 * 68 + 16 * ks + 8);
;                     const bf16x8 v0 = __builtin_bit_cast(bf16x8, (u32x4){va0[0], va0[1], va1[0], va1[1]}), v1 = __builtin_bit_cast(bf16x8, (u32x4){vb0[0], vb0[1], vb1[0], vb1[1]});
;                     const bf16x8 pfA = __builtin_bit_cast(bf16x8, pwA[k2]), pfB = __builtin_bit_cast(bf16x8, pwB[k2]);
.Lattn_fast_1:
.Laq1_b1:
	s_mul_i32 s4, s29, 0x3400
	v_add_u32_e32 v180, s4, v188
	s_mul_i32 s4, s29, 0x2200
	v_add_u32_e32 v177, s4, v198
	v_add_u32_e32 v178, 0x6800, v177
	ds_read_b128 v[248:251], v180
	ds_read_b128 v[158:161], v180 offset:32
	s_setprio 1
	s_waitcnt lgkmcnt(1)
	v_mfma_f32_32x32x16_bf16 v[96:111], v[248:251], v[132:135], v[0:15]
	v_mfma_f32_32x32x16_bf16 v[80:95], v[248:251], v[214:217], v[0:15]
	ds_read_b128 v[248:251], v180 offset:64
	s_waitcnt lgkmcnt(1)
	v_mfma_f32_32x32x16_bf16 v[96:111], v[158:161], v[136:139], v[96:111]
	v_mfma_f32_32x32x16_bf16 v[80:95], v[158:161], v[218:221], v[80:95]
	ds_read_b128 v[158:161], v180 offset:96
	s_waitcnt lgkmcnt(1)
	v_mfma_f32_32x32x16_bf16 v[96:111], v[248:251], v[140:143], v[96:111]
	v_mfma_f32_32x32x16_bf16 v[80:95], v[248:251], v[232:235], v[80:95]
	ds_read_b128 v[248:251], v180 offset:128
	s_waitcnt lgkmcnt(1)
	v_mfma_f32_32x32x16_bf16 v[96:111], v[158:161], v[144:147], v[96:111]
	v_mfma_f32_32x32x16_bf16 v[80:95], v[158:161], v[236:239], v[80:95]
	ds_read_b128 v[158:161], v180 offset:160
	s_waitcnt lgkmcnt(1)
	v_mfma_f32_32x32x16_bf16 v[96:111], v[248:251], v[206:209], v[96:111]
	v_mfma_f32_32x32x16_bf16 v[80:95], v[248:251], v[240:243], v[80:95]
	s_waitcnt lgkmcnt(0)
	v_mfma_f32_32x32x16_bf16 v[96:111], v[158:161], v[210:213], v[96:111]
	v_mfma_f32_32x32x16_bf16 v[80:95], v[158:161], v[244:247], v[80:95]
	ds_read_b64 v[248:249], v178 offset:0
	ds_read_b64 v[250:251], v178 offset:16
	ds_read_b64 v[158:159], v178 offset:4352
	ds_read_b64 v[160:161], v178 offset:4368
	s_setprio 0
	s_nop 5
	v_exp_f32_e32 v96, v96
	v_exp_f32_e32 v97, v97
	v_exp_f32_e32 v98, v98
	v_exp_f32_e32 v99, v99
	v_add_f32_e32 v182, v96, v97
	v_cvt_pk_bf16_f32 v96, v96, v97
	v_exp_f32_e32 v100, v100
	v_exp_f32_e32 v101, v101
	v_add_f32_e32 v182, v182, v98
	v_add_f32_e32 v182, v182, v99
	v_cvt_pk_bf16_f32 v97, v98, v99
	v_exp_f32_e32 v102, v102
	v_exp_f32_e32 v103, v103
	v_add_f32_e32 v182, v182, v100
	v_add_f32_e32 v182, v182, v101
	v_cvt_pk_bf16_f32 v98, v100, v101
	v_exp_f32_e32 v80, v80
	v_exp_f32_e32 v81, v81
	v_add_f32_e32 v182, v182, v102
	v_add_f32_e32 v182, v182, v103
	v_cvt_pk_bf16_f32 v99, v102, v103
	v_exp_f32_e32 v82, v82
	v_exp_f32_e32 v83, v83
	v_add_f32_e32 v162, v80, v81
	v_cvt_pk_bf16_f32 v80, v80, v81
	v_exp_f32_e32 v84, v84
	v_exp_f32_e32 v85, v85
	v_add_f32_e32 v162, v162, v82
	v_add_f32_e32 v162, v162, v83
	v_cvt_pk_bf16_f32 v81, v82, v83
	v_exp_f32_e32 v86, v86
	v_exp_f32_e32 v87, v87
	v_add_f32_e32 v162, v162, v84
	v_add_f32_e32 v162, v162, v85
	v_cvt_pk_bf16_f32 v82, v84, v85
	v_exp_f32_e32 v104, v104
	v_exp_f32_e32 v105, v105
	v_add_f32_e32 v162, v162, v86
	v_add_f32_e32 v162, v162, v87
	v_cvt_pk_bf16_f32 v83, v86, v87
	v_exp_f32_e32 v106, v106
	v_exp_f32_e32 v107, v107
	v_add_f32_e32 v182, v182, v104
	v_add_f32_e32 v182, v182, v105
	v_cvt_pk_bf16_f32 v100, v104, v105
	v_exp_f32_e32 v108, v108
	v_exp_f32_e32 v109, v109
	v_add_f32_e32 v182, v182, v106
	v_add_f32_e32 v182, v182, v107
	v_cvt_pk_bf16_f32 v101, v106, v107
	v_exp_f32_e32 v110, v110
	v_exp_f32_e32 v111, v111
	v_add_f32_e32 v182, v182, v108
	v_add_f32_e32 v182, v182, v109
	v_cvt_pk_bf16_f32 v102, v108, v109
	v_exp_f32_e32 v88, v88
	v_exp_f32_e32 v89, v89
	v_add_f32_e32 v182, v182, v110
	v_add_f32_e32 v182, v182, v111
	v_cvt_pk_bf16_f32 v103, v110, v111
	ds_read_b64 v[104:105], v178 offset:32
	ds_read_b64 v[106:107], v178 offset:48
	ds_read_b64 v[108:109], v178 offset:4384
	ds_read_b64 v[110:111], v178 offset:4400
	v_exp_f32_e32 v90, v90
	v_exp_f32_e32 v91, v91
	v_add_f32_e32 v162, v162, v88
	v_add_f32_e32 v162, v162, v89
	v_cvt_pk_bf16_f32 v84, v88, v89
	v_exp_f32_e32 v92, v92
	v_exp_f32_e32 v93, v93
	v_add_f32_e32 v162, v162, v90
	v_add_f32_e32 v162, v162, v91
	v_cvt_pk_bf16_f32 v85, v90, v91
	v_exp_f32_e32 v94, v94
	v_exp_f32_e32 v95, v95
	v_add_f32_e32 v162, v162, v92
	v_add_f32_e32 v162, v162, v93
	v_cvt_pk_bf16_f32 v86, v92, v93
	v_add_f32_e32 v162, v162, v94
	v_add_f32_e32 v162, v162, v95
	v_cvt_pk_bf16_f32 v87, v94, v95
	v_add_f32_e32 v157, v157, v182
	v_add_f32_e32 v156, v156, v162
	s_setprio 1
	s_waitcnt lgkmcnt(6)
	v_mfma_f32_32x32x16_bf16 v[64:79], v[248:251], v[96:99], v[64:79]
	v_mfma_f32_32x32x16_bf16 v[32:47], v[248:251], v[80:83], v[32:47]
	s_waitcnt lgkmcnt(4)
	v_mfma_f32_32x32x16_bf16 v[48:63], v[158:161], v[96:99], v[48:63]
	v_mfma_f32_32x32x16_bf16 v[16:31], v[158:161], v[80:83], v[16:31]
	ds_read_b128 v[248:251], v180 offset:6656
	ds_read_b128 v[158:161], v180 offset:6688
	s_waitcnt lgkmcnt(4)
	v_mfma_f32_32x32x16_bf16 v[64:79], v[104:107], v[100:103], v[64:79]
	s_waitcnt lgkmcnt(2)
	v_mfma_f32_32x32x16_bf16 v[48:63], v[108:111], v[100:103], v[48:63]
	v_mfma_f32_32x32x16_bf16 v[32:47], v[104:107], v[84:87], v[32:47]
	v_mfma_f32_32x32x16_bf16 v[16:31], v[108:111], v[84:87], v[16:31]
	s_setprio 1
	s_waitcnt lgkmcnt(1)
	v_mfma_f32_32x32x16_bf16 v[96:111], v[248:251], v[132:135], v[0:15]
	v_mfma_f32_32x32x16_bf16 v[80:95], v[248:251], v[214:217], v[0:15]
	ds_read_b128 v[248:251], v180 offset:6720
	s_waitcnt lgkmcnt(1)
	v_mfma_f32_32x32x16_bf16 v[96:111], v[158:161], v[136:139], v[96:111]
	v_mfma_f32_32x32x16_bf16 v[80:95], v[158:161], v[218:221], v[80:95]
	ds_read_b128 v[158:161], v180 offset:6752
	s_waitcnt lgkmcnt(1)
	v_mfma_f32_32x32x16_bf16 v[96:111], v[248:251], v[140:143], v[96:111]
	v_mfma_f32_32x32x16_bf16 v[80:95], v[248:251], v[232:235], v[80:95]
	ds_read_b128 v[248:251], v180 offset:6784
	s_waitcnt lgkmcnt(1)
	v_mfma_f32_32x32x16_bf16 v[96:111], v[158:161], v[144:147], v[96:111]
	v_mfma_f32_32x32x16_bf16 v[80:95], v[158:161], v[236:239], v[80:95]
	ds_read_b128 v[158:161], v180 offset:6816
	s_waitcnt lgkmcnt(1)
; #define LAS __attribute__((address_space(3)))
; __device__ __forceinline__ void attn_unit64(const bf16_t* Q, const bf16_t* K, const bf16_t* Vt, bf16_t* O, int bh, int qb8, float mfix, LAS unsigned char* lds) {
;     ...
;         if (t <= tmaxw) {
;             const LAS bf16_t* kp = Kb + buf * 6656 + r * 104 + 8 * hh;
;             const LAS bf16_t* vp = Vb + buf * 4352 + r * 68 + 4 * hh;
; #pragma unroll
;             for (int half = 0; half < 2; ++half) {
;                 f32x16 sA, sB;
; #pragma unroll
;                 for (int i = 0; i < 16; ++i) { sA[i] = -mfix; sB[i] = -mfix; }
; #pragma unroll
;                 for (int d0 = 0; d0 < 6; ++d0) { const bf16x8 a = *(const LAS bf16x8*)(kp + half * 32 * 104 + 16 * d0); const bf16x8 qa_ = Qs[512 * d0], qb_ = Qs[512 * (6 + d0)]; sA = MFMA32(a, qa_, sA); sB = MFMA32(a, qb_, sB); }
;                 if (t == tmaxw) {
;                     const int rowA = qw + r, rowB = qw + 32 + r;
; #pragma unroll
;                     for (int i = 0; i < 16; ++i) { const int kv = 64 * t + 32 * half + crow(i, hh); if (kv > rowA) sA[i] = -1e30f; if (kv > rowB) sB[i] = -1e30f; }
;                 }
;                 float la = 0.f, lb_ = 0.f;
; #pragma unroll
;                 for (int i = 0; i < 16; ++i) { sA[i] = __builtin_amdgcn_exp2f(sA[i]); sB[i] = __builtin_amdgcn_exp2f(sB[i]); la += sA[i]; lb_ += sB[i]; }
;                 lA += la; lB += lb_;
;                 u32x4 pwA[2], pwB[2];
; #pragma unroll
;                 for (int e = 0; e < 4; ++e) { pwA[0][e] = pk2(sA[2 * e], sA[2 * e + 1]); pwA[1][e] = pk2(sA[8 + 2 * e], sA[8 + 2 * e + 1]); pwB[0][e] = pk2(sB[2 * e], sB[2 * e + 1]); pwB[1][e] = pk2(sB[8 + 2 * e], sB[8 + 2 * e + 1]); }
; #pragma unroll
;                 for (int k2 = 0; k2 < 2; ++k2) { const int ks = 2 * half + k2;
;                     const u32x2 va0 = *(const LAS u32x2*)(vp + 16 * ks), va1 = *(const LAS u32x2*)(vp + 16 * ks + 8), vb0 = *(const LAS u32x2*)(vp + 32 * 68 + 16 * ks), vb1 = *(const LAS u32x2*)(vp + 32 * 68 + 16 * ks + 8);
;                     const bf16x8 v0 = __builtin_bit_cast(bf16x8, (u32x4){va0[0], va0[1], va1[0], va1[1]}), v1 = __builtin_bit_cast(bf16x8, (u32x4){vb0[0], vb0[1], vb1[0], vb1[1]});
;                     const bf16x8 pfA = __builtin_bit_cast(bf16x8, pwA[k2]), pfB = __builtin_bit_cast(bf16x8, pwB[k2]);
	v_mfma_f32_32x32x16_bf16 v[96:111], v[248:251], v[206:209], v[96:111]
	v_mfma_f32_32x32x16_bf16 v[80:95], v[248:251], v[240:243], v[80:95]
	s_waitcnt lgkmcnt(0)
	v_mfma_f32_32x32x16_bf16 v[96:111], v[158:161], v[210:213], v[96:111]
	v_mfma_f32_32x32x16_bf16 v[80:95], v[158:161], v[244:247], v[80:95]
	ds_read_b64 v[248:249], v178 offset:64
	ds_read_b64 v[250:251], v178 offset:80
	ds_read_b64 v[158:159], v178 offset:4416
	ds_read_b64 v[160:161], v178 offset:4432
	s_setprio 0
	s_nop 5
	v_exp_f32_e32 v96, v96
	v_exp_f32_e32 v97, v97
	v_exp_f32_e32 v98, v98
	v_exp_f32_e32 v99, v99
	v_add_f32_e32 v182, v96, v97
	v_cvt_pk_bf16_f32 v96, v96, v97
	v_exp_f32_e32 v100, v100
	v_exp_f32_e32 v101, v101
	v_add_f32_e32 v182, v182, v98
	v_add_f32_e32 v182, v182, v99
	v_cvt_pk_bf16_f32 v97, v98, v99
	v_exp_f32_e32 v102, v102
	v_exp_f32_e32 v103, v103
	v_add_f32_e32 v182, v182, v100
	v_add_f32_e32 v182, v182, v101
	v_cvt_pk_bf16_f32 v98, v100, v101
	v_exp_f32_e32 v80, v80
	v_exp_f32_e32 v81, v81
	v_add_f32_e32 v182, v182, v102
	v_add_f32_e32 v182, v182, v103
	v_cvt_pk_bf16_f32 v99, v102, v103
	v_exp_f32_e32 v82, v82
	v_exp_f32_e32 v83, v83
	v_add_f32_e32 v162, v80, v81
	v_cvt_pk_bf16_f32 v80, v80, v81
	v_exp_f32_e32 v84, v84
	v_exp_f32_e32 v85, v85
	v_add_f32_e32 v162, v162, v82
	v_add_f32_e32 v162, v162, v83
	v_cvt_pk_bf16_f32 v81, v82, v83
	v_exp_f32_e32 v86, v86
	v_exp_f32_e32 v87, v87
	v_add_f32_e32 v162, v162, v84
	v_add_f32_e32 v162, v162, v85
	v_cvt_pk_bf16_f32 v82, v84, v85
	v_exp_f32_e32 v104, v104
	v_exp_f32_e32 v105, v105
	v_add_f32_e32 v162, v162, v86
	v_add_f32_e32 v162, v162, v87
	v_cvt_pk_bf16_f32 v83, v86, v87
	v_exp_f32_e32 v106, v106
	v_exp_f32_e32 v107, v107
	v_add_f32_e32 v182, v182, v104
	v_add_f32_e32 v182, v182, v105
	v_cvt_pk_bf16_f32 v100, v104, v105
	v_exp_f32_e32 v108, v108
	v_exp_f32_e32 v109, v109
	v_add_f32_e32 v182, v182, v106
	v_add_f32_e32 v182, v182, v107
	v_cvt_pk_bf16_f32 v101, v106, v107
	v_exp_f32_e32 v110, v110
	v_exp_f32_e32 v111, v111
	v_add_f32_e32 v182, v182, v108
	v_add_f32_e32 v182, v182, v109
	v_cvt_pk_bf16_f32 v102, v108, v109
	v_exp_f32_e32 v88, v88
	v_exp_f32_e32 v89, v89
	v_add_f32_e32 v182, v182, v110
	v_add_f32_e32 v182, v182, v111
	v_cvt_pk_bf16_f32 v103, v110, v111
	ds_read_b64 v[104:105], v178 offset:96
	ds_read_b64 v[106:107], v178 offset:112
	ds_read_b64 v[108:109], v178 offset:4448
	ds_read_b64 v[110:111], v178 offset:4464
	v_exp_f32_e32 v90, v90
	v_exp_f32_e32 v91, v91
	v_add_f32_e32 v162, v162, v88
	v_add_f32_e32 v162, v162, v89
	v_cvt_pk_bf16_f32 v84, v88, v89
	v_exp_f32_e32 v92, v92
	v_exp_f32_e32 v93, v93
	v_add_f32_e32 v162, v162, v90
	v_add_f32_e32 v162, v162, v91
	v_cvt_pk_bf16_f32 v85, v90, v91
	v_exp_f32_e32 v94, v94
	v_exp_f32_e32 v95, v95
	v_add_f32_e32 v162, v162, v92
	v_add_f32_e32 v162, v162, v93
	v_cvt_pk_bf16_f32 v86, v92, v93
	v_add_f32_e32 v162, v162, v94
	v_add_f32_e32 v162, v162, v95
	v_cvt_pk_bf16_f32 v87, v94, v95
	v_add_f32_e32 v157, v157, v182
	v_add_f32_e32 v156, v156, v162
	s_setprio 1
	s_waitcnt lgkmcnt(6)
	v_mfma_f32_32x32x16_bf16 v[64:79], v[248:251], v[96:99], v[64:79]
	v_mfma_f32_32x32x16_bf16 v[32:47], v[248:251], v[80:83], v[32:47]
	s_waitcnt lgkmcnt(4)
	v_mfma_f32_32x32x16_bf16 v[48:63], v[158:161], v[96:99], v[48:63]
	v_mfma_f32_32x32x16_bf16 v[16:31], v[158:161], v[80:83], v[16:31]
	s_waitcnt lgkmcnt(2)
	v_mfma_f32_32x32x16_bf16 v[64:79], v[104:107], v[100:103], v[64:79]
	s_waitcnt lgkmcnt(0)
	v_mfma_f32_32x32x16_bf16 v[48:63], v[108:111], v[100:103], v[48:63]
	v_mfma_f32_32x32x16_bf16 v[32:47], v[104:107], v[84:87], v[32:47]
	v_mfma_f32_32x32x16_bf16 v[16:31], v[108:111], v[84:87], v[16:31]
	s_setprio 0
.Laq1_b5:
	s_branch .Lattn_join_1
.LBB0_809:
	ds_bpermute_b32 v80, v187, v157
	v_or_b32_e32 v164, s48, v195
	v_lshlrev_b32_e32 v128, 1, v199
	v_mov_b32_e32 v129, 0
	ds_bpermute_b32 v88, v187, v156
	s_waitcnt lgkmcnt(1)
	v_add_f32_e32 v80, v157, v80
	v_div_scale_f32 v81, s[4:5], v80, v80, 1.0
	v_rcp_f32_e32 v82, v81
	v_div_scale_f32 v83, vcc, 1.0, v80, 1.0
	v_readfirstlane_b32 s16, v254
	v_fma_f32 v84, -v81, v82, 1.0
	v_fmac_f32_e32 v82, v84, v82
	v_mul_f32_e32 v84, v83, v82
	v_fma_f32 v85, -v81, v84, v83
	v_fmac_f32_e32 v84, v85, v82
	v_fma_f32 v81, -v81, v84, v83
	v_div_fmas_f32 v81, v81, v82, v84
	v_add_u32_e32 v82, s3, v164
	v_div_fixup_f32 v80, v81, v80, 1.0
	v_ashrrev_i32_e32 v83, 31, v82
	v_lshlrev_b64 v[82:83], 11, v[82:83]
	v_pk_mul_f32 v[70:71], v[70:71], v[80:81] op_sel_hi:[1,0]
	v_pk_mul_f32 v[68:69], v[68:69], v[80:81] op_sel_hi:[1,0]
	v_pk_mul_f32 v[84:85], v[66:67], v[80:81] op_sel_hi:[1,0]
	v_pk_mul_f32 v[86:87], v[64:65], v[80:81] op_sel_hi:[1,0]
	v_lshl_add_u64 v[82:83], s[10:11], 0, v[82:83]
	v_cvt_pk_bf16_f32 v67, v70, v71
	v_cvt_pk_bf16_f32 v66, v68, v69
	v_cvt_pk_bf16_f32 v65, v84, v85
	v_cvt_pk_bf16_f32 v64, v86, v87
	v_lshl_add_u64 v[82:83], v[82:83], 0, v[128:129]
	s_nop 0
	v_permlane32_swap_b32_e32 v64, v66
	v_permlane32_swap_b32_e32 v65, v67
	global_store_dwordx4 v[82:83], v[64:67], off
	v_pk_mul_f32 v[68:69], v[76:77], v[80:81] op_sel_hi:[1,0]
	v_pk_mul_f32 v[70:71], v[74:75], v[80:81] op_sel_hi:[1,0]
	v_pk_mul_f32 v[64:65], v[78:79], v[80:81] op_sel_hi:[1,0]
	v_pk_mul_f32 v[72:73], v[72:73], v[80:81] op_sel_hi:[1,0]
	v_cvt_pk_bf16_f32 v67, v64, v65
	v_cvt_pk_bf16_f32 v66, v68, v69
	v_cvt_pk_bf16_f32 v65, v70, v71
	v_cvt_pk_bf16_f32 v64, v72, v73
	s_nop 1
	v_permlane32_swap_b32_e32 v64, v66
	v_permlane32_swap_b32_e32 v65, v67
	global_store_dwordx4 v[82:83], v[64:67], off offset:32
	v_pk_mul_f32 v[54:55], v[54:55], v[80:81] op_sel_hi:[1,0]
	v_pk_mul_f32 v[52:53], v[52:53], v[80:81] op_sel_hi:[1,0]
	v_pk_mul_f32 v[64:65], v[50:51], v[80:81] op_sel_hi:[1,0]
	v_pk_mul_f32 v[66:67], v[48:49], v[80:81] op_sel_hi:[1,0]
	v_cvt_pk_bf16_f32 v51, v54, v55
	v_cvt_pk_bf16_f32 v50, v52, v53
	v_cvt_pk_bf16_f32 v49, v64, v65
	v_cvt_pk_bf16_f32 v48, v66, v67
	s_nop 1
	v_permlane32_swap_b32_e32 v48, v50
	v_permlane32_swap_b32_e32 v49, v51
	v_pk_mul_f32 v[52:53], v[60:61], v[80:81] op_sel_hi:[1,0]
	global_store_dwordx4 v[82:83], v[48:51], off offset:64
	v_pk_mul_f32 v[54:55], v[58:59], v[80:81] op_sel_hi:[1,0]
	v_pk_mul_f32 v[56:57], v[56:57], v[80:81] op_sel_hi:[1,0]
	v_cvt_pk_bf16_f32 v50, v52, v53
	s_waitcnt lgkmcnt(0)
; #define LAS __attribute__((address_space(3)))
; __device__ __forceinline__ void attn_unit64(const bf16_t* Q, const bf16_t* K, const bf16_t* Vt, bf16_t* O, int bh, int qb8, float mfix, LAS unsigned char* lds) {
;     ...
;     const bf16_t* Qh = Q + (size_t)bh * SEQ * 96; const bf16_t* Kh = K + (size_t)bh * SEQ * 96; const bf16_t* Vh = Vt + (size_t)(bh & 7) * 64 * T + (size_t)(bh >> 3) * SEQ;
;     const int q0 = qb8 * 512, qw = q0 + wid * 64, NTL = 8 * (qb8 + 1), tmaxw = 8 * qb8 + wid;
;     LAS bf16x8* Qs = (LAS bf16x8*)(lds + 2 * 64 * 104 * 2 + 2 * 64 * 68 * 2) + tid;
; #pragma unroll
;     for (int d0 = 0; d0 < 6; ++d0) { Qs[512 * d0] = __builtin_nontemporal_load((const bf16x8*)(Qh + (size_t)(qw + r) * 96 + 16 * d0 + 8 * hh)); Qs[512 * (6 + d0)] = __builtin_nontemporal_load((const bf16x8*)(Qh + (size_t)(qw + 32 + r) * 96 + 16 * d0 + 8 * hh)); }
;     f32x16 oA0, oA1, oB0, oB1;
; #pragma unroll
;     for (int i = 0; i < 16; ++i) { oA0[i] = 0.f; oA1[i] = 0.f; oB0[i] = 0.f; oB1[i] = 0.f; }
;     float lA = 0.f, lB = 0.f;
;     const int c2 = 512 + tid, kr1 = tid / 12, kc1 = tid % 12, kr2 = c2 / 12, kc2 = c2 % 12, vr = tid >> 3, vc = tid & 7;
;     u32x4 kA, kB = {0u, 0u, 0u, 0u}, vA;
;     ...
;     const float ltA = lA + __shfl_xor(lA, 32), ltB = lB + __shfl_xor(lB, 32), invA = 1.0f / ltA, invB = 1.0f / ltB;
;     const int b = bh >> 3, head = bh & 7;
;     ...
;     { bf16_t* rowA = O + (size_t)(b * SEQ + qw + r) * 1024 + head * 64; ATT_OSTORE(oA0, oA1, invA, rowA); ATT_OSTORE(oB0, oB1, invB, rowA + (size_t)32 * 1024); }
	v_add_f32_e32 v52, v156, v88
	v_pk_mul_f32 v[48:49], v[62:63], v[80:81] op_sel_hi:[1,0]
	v_div_scale_f32 v53, s[4:5], v52, v52, 1.0
	v_cvt_pk_bf16_f32 v51, v48, v49
	v_cvt_pk_bf16_f32 v49, v54, v55
	v_rcp_f32_e32 v54, v53
	v_cvt_pk_bf16_f32 v48, v56, v57
	s_nop 1
	v_permlane32_swap_b32_e32 v48, v50
	v_permlane32_swap_b32_e32 v49, v51
	global_store_dwordx4 v[82:83], v[48:51], off offset:96
	s_mov_b32 s3, 0x10000
	s_mov_b64 s[4:5], 0x10000
	v_fma_f32 v48, -v53, v54, 1.0
	v_fmac_f32_e32 v54, v48, v54
	v_div_scale_f32 v48, vcc, 1.0, v52, 1.0
	v_mul_f32_e32 v49, v48, v54
	v_fma_f32 v50, -v53, v49, v48
	v_fmac_f32_e32 v49, v50, v54
	v_fma_f32 v48, -v53, v49, v48
	v_div_fmas_f32 v48, v48, v54, v49
	v_div_fixup_f32 v48, v48, v52, 1.0
	v_pk_mul_f32 v[38:39], v[38:39], v[48:49] op_sel_hi:[1,0]
	v_pk_mul_f32 v[36:37], v[36:37], v[48:49] op_sel_hi:[1,0]
	v_pk_mul_f32 v[52:53], v[34:35], v[48:49] op_sel_hi:[1,0]
	v_pk_mul_f32 v[54:55], v[32:33], v[48:49] op_sel_hi:[1,0]
	v_cvt_pk_bf16_f32 v35, v38, v39
	v_cvt_pk_bf16_f32 v34, v36, v37
	v_cvt_pk_bf16_f32 v33, v52, v53
	v_cvt_pk_bf16_f32 v32, v54, v55
	v_add_co_u32_e32 v36, vcc, s3, v82
	s_nop 0
	v_permlane32_swap_b32_e32 v32, v34
	v_permlane32_swap_b32_e32 v33, v35
	v_addc_co_u32_e32 v37, vcc, 0, v83, vcc
	global_store_dwordx4 v[36:37], v[32:35], off
	v_pk_mul_f32 v[36:37], v[44:45], v[48:49] op_sel_hi:[1,0]
	v_pk_mul_f32 v[38:39], v[42:43], v[48:49] op_sel_hi:[1,0]
	v_pk_mul_f32 v[32:33], v[46:47], v[48:49] op_sel_hi:[1,0]
	v_pk_mul_f32 v[40:41], v[40:41], v[48:49] op_sel_hi:[1,0]
	v_cvt_pk_bf16_f32 v35, v32, v33
	v_cvt_pk_bf16_f32 v34, v36, v37
	v_cvt_pk_bf16_f32 v33, v38, v39
	v_cvt_pk_bf16_f32 v32, v40, v41
	v_lshl_add_u64 v[50:51], v[82:83], 0, s[4:5]
	s_nop 0
	v_permlane32_swap_b32_e32 v32, v34
	v_permlane32_swap_b32_e32 v33, v35
	global_store_dwordx4 v[50:51], v[32:35], off offset:32
	v_pk_mul_f32 v[22:23], v[22:23], v[48:49] op_sel_hi:[1,0]
	v_pk_mul_f32 v[20:21], v[20:21], v[48:49] op_sel_hi:[1,0]
	v_pk_mul_f32 v[32:33], v[18:19], v[48:49] op_sel_hi:[1,0]
	v_pk_mul_f32 v[34:35], v[16:17], v[48:49] op_sel_hi:[1,0]
	v_cvt_pk_bf16_f32 v19, v22, v23
	v_cvt_pk_bf16_f32 v18, v20, v21
	v_cvt_pk_bf16_f32 v17, v32, v33
	v_cvt_pk_bf16_f32 v16, v34, v35
	s_lshl_b32 s26, s42, 9
	s_nop 0
	v_permlane32_swap_b32_e32 v16, v18
	v_permlane32_swap_b32_e32 v17, v19
	s_and_b32 s3, s16, 0xffffffc0
	global_store_dwordx4 v[50:51], v[16:19], off offset:64
	v_pk_mul_f32 v[20:21], v[28:29], v[48:49] op_sel_hi:[1,0]
	v_pk_mul_f32 v[22:23], v[26:27], v[48:49] op_sel_hi:[1,0]
	v_pk_mul_f32 v[16:17], v[30:31], v[48:49] op_sel_hi:[1,0]
	v_pk_mul_f32 v[24:25], v[24:25], v[48:49] op_sel_hi:[1,0]
	s_add_i32 s3, s3, s26
	v_cvt_pk_bf16_f32 v19, v16, v17
	v_cvt_pk_bf16_f32 v18, v20, v21
	v_cvt_pk_bf16_f32 v17, v22, v23
	v_cvt_pk_bf16_f32 v16, v24, v25
	v_or_b32_e32 v165, s3, v195
	s_nop 0
	v_permlane32_swap_b32_e32 v16, v18
	v_permlane32_swap_b32_e32 v17, v19
	s_movk_i32 s17, 0xc0
	v_or_b32_e32 v166, 32, v165
	global_store_dwordx4 v[50:51], v[16:19], off offset:96
	v_mad_i64_i32 v[56:57], s[4:5], v165, s17, v[154:155]
	v_mad_i64_i32 v[60:61], s[4:5], v166, s17, v[154:155]
	global_load_dwordx4 v[16:19], v[56:57], off nt
	global_load_dwordx4 v[20:23], v[60:61], off nt
	global_load_dwordx4 v[24:27], v[56:57], off offset:32 nt
	global_load_dwordx4 v[28:31], v[60:61], off offset:32 nt
	global_load_dwordx4 v[32:35], v[56:57], off offset:64 nt
	global_load_dwordx4 v[36:39], v[60:61], off offset:64 nt
	global_load_dwordx4 v[40:43], v[56:57], off offset:96 nt
	global_load_dwordx4 v[44:47], v[60:61], off offset:96 nt
	global_load_dwordx4 v[48:51], v[56:57], off offset:128 nt
	global_load_dwordx4 v[52:55], v[60:61], off offset:128 nt
	s_nop 0
	global_load_dwordx4 v[56:59], v[56:57], off offset:160 nt
	s_nop 0
	global_load_dwordx4 v[60:63], v[60:61], off offset:160 nt
	s_nop 0
	global_load_dwordx4 v[112:115], v[152:153], off
	s_waitcnt vmcnt(22)
	v_mov_b32_e32 v116, v129
	v_mov_b32_e32 v117, v129
	v_mov_b32_e32 v118, v129
	v_mov_b32_e32 v119, v129
	s_waitcnt vmcnt(12)
	ds_write_b128 v200, v[16:19] offset:44032
	s_waitcnt vmcnt(11)
	ds_write_b128 v201, v[20:23] offset:49152
	s_waitcnt vmcnt(10)
	ds_write_b128 v200, v[24:27] offset:52224
	s_waitcnt vmcnt(9)
	ds_write_b128 v201, v[28:31] offset:57344
	s_waitcnt vmcnt(8)
	ds_write_b128 v200, v[32:35] offset:60416
	s_waitcnt vmcnt(7)
	ds_write_b128 v202, v[36:39]
	s_waitcnt vmcnt(6)
	ds_write_b128 v201, v[40:43] offset:24576
	s_waitcnt vmcnt(5)
	ds_write_b128 v203, v[44:47]
	s_waitcnt vmcnt(4)
	ds_write_b128 v201, v[48:51] offset:32768
	s_waitcnt vmcnt(3)
	ds_write_b128 v204, v[52:55]
	s_waitcnt vmcnt(2)
	ds_write_b128 v201, v[56:59] offset:40960
	s_waitcnt vmcnt(1)
	ds_write_b128 v205, v[60:63]
	s_and_saveexec_b64 s[4:5], s[0:1]
	s_cbranch_execz .LBB0_811
	global_load_dwordx4 v[116:119], v[148:149], off
; #define LAS __attribute__((address_space(3)))
; #define MFMA32(a, b, c) __builtin_amdgcn_mfma_f32_32x32x16_bf16((a), (b), (c), 0, 0, 0)
; #define ATT_LOADG(t) do { kA = *(const u32x4*)(Kh + (size_t)(t) * 6144 + tid * 8); if (tid < 256) kB = *(const u32x4*)(Kh + (size_t)(t) * 6144 + c2 * 8); \
;         vA = *(const u32x4*)(Vh + (size_t)vr * T + 64 * (t) + vc * 8); } while (0)
; #define ATT_STORE(buf) do { *(LAS u32x4*)(Kb + (buf) * 6656 + kr1 * 104 + kc1 * 8) = kA; if (tid < 256) *(LAS u32x4*)(Kb + (buf) * 6656 + kr2 * 104 + kc2 * 8) = kB; \
;         *(LAS u32x2*)(Vb + (buf) * 4352 + vr * 68 + vc * 8) = (u32x2){vA[0], vA[1]}; *(LAS u32x2*)(Vb + (buf) * 4352 + vr * 68 + vc * 8 + 4) = (u32x2){vA[2], vA[3]}; } while (0)
; #define ATT_LOADG(t) do { kA = *(const u32x4*)(Kh + (size_t)(t) * 6144 + tid * 8); if (tid < 256) kB = *(const u32x4*)(Kh + (size_t)(t) * 6144 + c2 * 8); \
;         vA = *(const u32x4*)(Vh + (size_t)vr * T + 64 * (t) + vc * 8); } while (0)
; #define ATT_STORE(buf) do { *(LAS u32x4*)(Kb + (buf) * 6656 + kr1 * 104 + kc1 * 8) = kA; if (tid < 256) *(LAS u32x4*)(Kb + (buf) * 6656 + kr2 * 104 + kc2 * 8) = kB; \
;         *(LAS u32x2*)(Vb + (buf) * 4352 + vr * 68 + vc * 8) = (u32x2){vA[0], vA[1]}; *(LAS u32x2*)(Vb + (buf) * 4352 + vr * 68 + vc * 8 + 4) = (u32x2){vA[2], vA[3]}; } while (0)
; __device__ __forceinline__ void attn_unit64(const bf16_t* Q, const bf16_t* K, const bf16_t* Vt, bf16_t* O, int bh, int qb8, float mfix, LAS unsigned char* lds) {
;     ...
; #pragma unroll
;     for (int i = 0; i < 16; ++i) { oA0[i] = 0.f; oA1[i] = 0.f; oB0[i] = 0.f; oB1[i] = 0.f; }
;     float lA = 0.f, lB = 0.f;
;     const int c2 = 512 + tid, kr1 = tid / 12, kc1 = tid % 12, kr2 = c2 / 12, kc2 = c2 % 12, vr = tid >> 3, vc = tid & 7;
;     u32x4 kA, kB = {0u, 0u, 0u, 0u}, vA;
;     ...
;     ATT_LOADG(0); ATT_STORE(0); __syncthreads();
;     ...
;                 for (int d0 = 0; d0 < 6; ++d0) { const bf16x8 a = *(const LAS bf16x8*)(kp + half * 32 * 104 + 16 * d0); const bf16x8 qa_ = Qs[512 * d0], qb_ = Qs[512 * (6 + d0)]; sA = MFMA32(a, qa_, sA); sB = MFMA32(a, qb_, sB); }
.LBB0_811:
	s_or_b64 exec, exec, s[4:5]
	global_load_dwordx4 v[120:123], v[150:151], off
	s_waitcnt vmcnt(1)
	ds_write_b128 v197, v[112:115]
	s_and_saveexec_b64 s[4:5], s[0:1]
	v_add_u32_e32 v16, v196, v190
	ds_write_b128 v16, v[116:119]
	s_or_b64 exec, exec, s[4:5]
	v_mov_b32_e32 v130, 0
	v_add_u32_e32 v16, 0x6800, v189
	v_mov_b32_e32 v64, v130
	v_mov_b32_e32 v65, v130
	s_lshl_b32 s25, s42, 3
	s_lshr_b32 s24, s16, 6
	s_waitcnt vmcnt(0)
	ds_write2_b64 v16, v[120:121], v[122:123] offset1:1
	v_mov_b32_e32 v66, v130
	v_mov_b32_e32 v67, v130
	v_mov_b32_e32 v68, v130
	v_mov_b32_e32 v69, v130
	v_mov_b32_e32 v70, v130
	v_mov_b32_e32 v71, v130
	v_mov_b32_e32 v72, v130
	v_mov_b32_e32 v73, v130
	v_mov_b32_e32 v74, v130
	v_mov_b32_e32 v75, v130
	v_mov_b32_e32 v76, v130
	v_mov_b32_e32 v77, v130
	v_mov_b32_e32 v78, v130
	v_mov_b32_e32 v79, v130
	v_mov_b64_e32 v[48:49], v[64:65]
	v_mov_b64_e32 v[32:33], v[64:65]
	v_mov_b64_e32 v[16:17], v[64:65]
	s_add_i32 s24, s24, s25
	s_add_i32 s25, s25, 8
	s_addk_i32 s26, 0x200
	s_mov_b32 s27, 0
	v_mov_b32_e32 v131, v130
	s_mov_b64 s[16:17], 0x3000
	s_mov_b64 s[18:19], 0x80
	v_mov_b32_e32 v129, 0xf149f2ca
	v_mov_b64_e32 v[50:51], v[66:67]
	v_mov_b64_e32 v[52:53], v[68:69]
	v_mov_b64_e32 v[54:55], v[70:71]
	v_mov_b64_e32 v[56:57], v[72:73]
	v_mov_b64_e32 v[58:59], v[74:75]
	v_mov_b64_e32 v[60:61], v[76:77]
	v_mov_b64_e32 v[62:63], v[78:79]
	v_mov_b64_e32 v[34:35], v[66:67]
	v_mov_b64_e32 v[36:37], v[68:69]
	v_mov_b64_e32 v[38:39], v[70:71]
	v_mov_b64_e32 v[40:41], v[72:73]
	v_mov_b64_e32 v[42:43], v[74:75]
	v_mov_b64_e32 v[44:45], v[76:77]
	v_mov_b64_e32 v[46:47], v[78:79]
	v_mov_b64_e32 v[18:19], v[66:67]
	v_mov_b64_e32 v[20:21], v[68:69]
	v_mov_b64_e32 v[22:23], v[70:71]
	v_mov_b64_e32 v[24:25], v[72:73]
	v_mov_b64_e32 v[26:27], v[74:75]
	v_mov_b64_e32 v[28:29], v[76:77]
	v_mov_b64_e32 v[30:31], v[78:79]
	s_mov_b32 s33, 0
	s_waitcnt lgkmcnt(0)
	s_barrier
	ds_read_b128 v[132:135], v200 offset:44032
	ds_read_b128 v[136:139], v200 offset:52224
	ds_read_b128 v[140:143], v200 offset:60416
	ds_read_b128 v[144:147], v201 offset:24576
	ds_read_b128 v[206:209], v201 offset:32768
	ds_read_b128 v[210:213], v201 offset:40960
	ds_read_b128 v[214:217], v201 offset:49152
	ds_read_b128 v[218:221], v201 offset:57344
	ds_read_b128 v[232:235], v202
	ds_read_b128 v[236:239], v203
	ds_read_b128 v[240:243], v204
	ds_read_b128 v[244:247], v205
	s_waitcnt lgkmcnt(0)

; #define LAS __attribute__((address_space(3)))
; #define MFMA32(a, b, c) __builtin_amdgcn_mfma_f32_32x32x16_bf16((a), (b), (c), 0, 0, 0)
; __device__ __forceinline__ int crow(int r, int hi) { return (r & 3) + 8 * (r >> 2) + 4 * hi; }
; __device__ __forceinline__ void attn_unit64(const bf16_t* Q, const bf16_t* K, const bf16_t* Vt, bf16_t* O, int bh, int qb8, float mfix, LAS unsigned char* lds) {
;     ...
;         if (t <= tmaxw) {
;             const LAS bf16_t* kp = Kb + buf * 6656 + r * 104 + 8 * hh;
;             const LAS bf16_t* vp = Vb + buf * 4352 + r * 68 + 4 * hh;
; #pragma unroll
;             for (int half = 0; half < 2; ++half) {
;                 f32x16 sA, sB;
; #pragma unroll
;                 for (int i = 0; i < 16; ++i) { sA[i] = -mfix; sB[i] = -mfix; }
; #pragma unroll
;                 for (int d0 = 0; d0 < 6; ++d0) { const bf16x8 a = *(const LAS bf16x8*)(kp + half * 32 * 104 + 16 * d0); const bf16x8 qa_ = Qs[512 * d0], qb_ = Qs[512 * (6 + d0)]; sA = MFMA32(a, qa_, sA); sB = MFMA32(a, qb_, sB); }
;                 if (t == tmaxw) {
;                     const int rowA = qw + r, rowB = qw + 32 + r;
; #pragma unroll
;                     for (int i = 0; i < 16; ++i) { const int kv = 64 * t + 32 * half + crow(i, hh); if (kv > rowA) sA[i] = -1e30f; if (kv > rowB) sB[i] = -1e30f; }
;                 }
.LBB0_820:
	s_cmp_lt_u32 s33, s24
	s_cbranch_scc1 .Lattn_fast_2
	s_mul_i32 s4, s29, 0x3400
	v_add_u32_e32 v170, s4, v188
	ds_read_b128 v[132:135], v170
	ds_read_b128 v[80:83], v200 offset:44032
	ds_read_b128 v[136:139], v200 offset:52224
	ds_read_b128 v[140:143], v170 offset:32
	ds_read_b128 v[144:147], v201 offset:49152
	ds_read_b128 v[148:151], v201 offset:40960
	s_cmp_eq_u32 s24, s33
	s_waitcnt lgkmcnt(4)
	v_mfma_f32_32x32x16_bf16 v[96:111], v[132:135], v[80:83], v[0:15]
	v_add_u32_e32 v169, s27, v194
	s_cselect_b64 s[22:23], -1, 0
	s_cmp_lg_u32 s24, s33
	v_cmp_le_i32_e32 vcc, v169, v165
	s_waitcnt lgkmcnt(1)
	v_mfma_f32_32x32x16_bf16 v[80:95], v[132:135], v[144:147], v[0:15]
	v_mfma_f32_32x32x16_bf16 v[96:111], v[140:143], v[136:139], v[96:111]
	ds_read_b128 v[132:135], v201 offset:57344
	ds_read_b128 v[136:139], v201 offset:24576
	s_waitcnt lgkmcnt(1)
	v_mfma_f32_32x32x16_bf16 v[80:95], v[140:143], v[132:135], v[80:95]
	ds_read_b128 v[132:135], v170 offset:64
	ds_read_b128 v[140:143], v200 offset:60416
	ds_read_b128 v[144:147], v170 offset:96
	ds_read_b128 v[152:155], v201 offset:32768
	s_waitcnt lgkmcnt(2)
	v_mfma_f32_32x32x16_bf16 v[96:111], v[132:135], v[140:143], v[96:111]
	ds_read_b128 v[140:143], v202
	ds_read_b128 v[156:159], v203
	s_waitcnt lgkmcnt(1)
	v_mfma_f32_32x32x16_bf16 v[80:95], v[132:135], v[140:143], v[80:95]
	v_mfma_f32_32x32x16_bf16 v[96:111], v[144:147], v[136:139], v[96:111]
	ds_read_b128 v[132:135], v170 offset:128
	ds_read_b128 v[136:139], v170 offset:160
	s_waitcnt lgkmcnt(2)
	v_mfma_f32_32x32x16_bf16 v[80:95], v[144:147], v[156:159], v[80:95]
	ds_read_b128 v[140:143], v204
	ds_read_b128 v[144:147], v205
	s_waitcnt lgkmcnt(3)
	v_mfma_f32_32x32x16_bf16 v[96:111], v[132:135], v[152:155], v[96:111]
	s_waitcnt lgkmcnt(1)
	v_mfma_f32_32x32x16_bf16 v[80:95], v[132:135], v[140:143], v[80:95]
	v_mfma_f32_32x32x16_bf16 v[96:111], v[136:139], v[148:151], v[96:111]
	s_waitcnt lgkmcnt(0)
	v_mfma_f32_32x32x16_bf16 v[80:95], v[136:139], v[144:147], v[80:95]
	s_cbranch_scc1 .LBB0_822
	s_nop 8
	v_cndmask_b32_e32 v96, v129, v96, vcc
	v_cmp_lt_i32_e32 vcc, v169, v166
	v_add_u32_e32 v132, 2, v169
	v_cmp_lt_i32_e64 s[4:5], v169, v165
	v_cndmask_b32_e32 v81, v129, v81, vcc
	v_cmp_le_i32_e32 vcc, v169, v166
	v_cndmask_b32_e64 v97, v129, v97, s[4:5]
	s_nop 0
	v_cndmask_b32_e32 v80, v129, v80, vcc
	v_cmp_le_i32_e32 vcc, v132, v165
	s_nop 1
	v_cndmask_b32_e32 v98, v129, v98, vcc
	v_cmp_le_i32_e32 vcc, v132, v166
	v_add_u32_e32 v132, 3, v169
	s_nop 0
	v_cndmask_b32_e32 v82, v129, v82, vcc
	v_cmp_le_i32_e32 vcc, v132, v165
	s_nop 1
	v_cndmask_b32_e32 v99, v129, v99, vcc
	v_cmp_le_i32_e32 vcc, v132, v166
	v_add_u32_e32 v132, 8, v169
	s_nop 0
	v_cndmask_b32_e32 v83, v129, v83, vcc
	v_cmp_le_i32_e32 vcc, v132, v165
	s_nop 1
	v_cndmask_b32_e32 v100, v129, v100, vcc
	v_cmp_le_i32_e32 vcc, v132, v166
	v_add_u32_e32 v132, 9, v169
	s_nop 0
	v_cndmask_b32_e32 v84, v129, v84, vcc
	v_cmp_le_i32_e32 vcc, v132, v165
	s_nop 1
	v_cndmask_b32_e32 v101, v129, v101, vcc
	v_cmp_le_i32_e32 vcc, v132, v166
	v_add_u32_e32 v132, 10, v169
	s_nop 0
	v_cndmask_b32_e32 v85, v129, v85, vcc
	v_cmp_le_i32_e32 vcc, v132, v165
	s_nop 1
	v_cndmask_b32_e32 v102, v129, v102, vcc
	v_cmp_le_i32_e32 vcc, v132, v166
	v_add_u32_e32 v132, 11, v169
	s_nop 0
	v_cndmask_b32_e32 v86, v129, v86, vcc
	v_cmp_le_i32_e32 vcc, v132, v165
	s_nop 1
	v_cndmask_b32_e32 v103, v129, v103, vcc
	v_cmp_le_i32_e32 vcc, v132, v166
	v_add_u32_e32 v132, 16, v169
	s_nop 0
	v_cndmask_b32_e32 v87, v129, v87, vcc
	v_cmp_le_i32_e32 vcc, v132, v165
	s_nop 1
	v_cndmask_b32_e32 v104, v129, v104, vcc
	v_cmp_le_i32_e32 vcc, v132, v166
	v_add_u32_e32 v132, 17, v169
	s_nop 0
	v_cndmask_b32_e32 v88, v129, v88, vcc
	v_cmp_le_i32_e32 vcc, v132, v165
	s_nop 1
	v_cndmask_b32_e32 v105, v129, v105, vcc
	v_cmp_le_i32_e32 vcc, v132, v166
	v_add_u32_e32 v132, 18, v169
	s_nop 0
	v_cndmask_b32_e32 v89, v129, v89, vcc
	v_cmp_le_i32_e32 vcc, v132, v165
	s_nop 1
	v_cndmask_b32_e32 v106, v129, v106, vcc
	v_cmp_le_i32_e32 vcc, v132, v166
	v_add_u32_e32 v132, 19, v169
	s_nop 0
	v_cndmask_b32_e32 v90, v129, v90, vcc
	v_cmp_le_i32_e32 vcc, v132, v165
	s_nop 1
	v_cndmask_b32_e32 v107, v129, v107, vcc
	v_cmp_le_i32_e32 vcc, v132, v166
	v_add_u32_e32 v132, 24, v169
	s_nop 0
	v_cndmask_b32_e32 v91, v129, v91, vcc
	v_cmp_le_i32_e32 vcc, v132, v165
	s_nop 1
	v_cndmask_b32_e32 v108, v129, v108, vcc
	v_cmp_le_i32_e32 vcc, v132, v166
	v_add_u32_e32 v132, 25, v169
	s_nop 0
	v_cndmask_b32_e32 v92, v129, v92, vcc
	v_cmp_le_i32_e32 vcc, v132, v165
	s_nop 1
	v_cndmask_b32_e32 v109, v129, v109, vcc
	v_cmp_le_i32_e32 vcc, v132, v166
	v_add_u32_e32 v132, 26, v169
	s_nop 0
	v_cndmask_b32_e32 v93, v129, v93, vcc
	v_cmp_le_i32_e32 vcc, v132, v165
	s_nop 1
	v_cndmask_b32_e32 v110, v129, v110, vcc
	v_cmp_le_i32_e32 vcc, v132, v166
	v_add_u32_e32 v132, 27, v169
	s_nop 0
	v_cndmask_b32_e32 v94, v129, v94, vcc
	v_cmp_le_i32_e32 vcc, v132, v165
	s_nop 1
	v_cndmask_b32_e32 v111, v129, v111, vcc
	v_cmp_le_i32_e32 vcc, v132, v166
	s_nop 1
	v_cndmask_b32_e32 v95, v129, v95, vcc

; #define LAS __attribute__((address_space(3)))
; __device__ __forceinline__ unsigned pk2(float lo, float hi) { f32x2_t v = {lo, hi}; bf16x2_t b = __builtin_convertvector(v, bf16x2_t); return __builtin_bit_cast(unsigned, b); }
; #define MFMA32(a, b, c) __builtin_amdgcn_mfma_f32_32x32x16_bf16((a), (b), (c), 0, 0, 0)
; #define ATT_STORE(buf) do { *(LAS u32x4*)(Kb + (buf) * 6656 + kr1 * 104 + kc1 * 8) = kA; if (tid < 256) *(LAS u32x4*)(Kb + (buf) * 6656 + kr2 * 104 + kc2 * 8) = kB; \
;         *(LAS u32x2*)(Vb + (buf) * 4352 + vr * 68 + vc * 8) = (u32x2){vA[0], vA[1]}; *(LAS u32x2*)(Vb + (buf) * 4352 + vr * 68 + vc * 8 + 4) = (u32x2){vA[2], vA[3]}; } while (0)
; __device__ __forceinline__ void attn_unit64(const bf16_t* Q, const bf16_t* K, const bf16_t* Vt, bf16_t* O, int bh, int qb8, float mfix, LAS unsigned char* lds) {
;     ...
;                 float la = 0.f, lb_ = 0.f;
; #pragma unroll
;                 for (int i = 0; i < 16; ++i) { sA[i] = __builtin_amdgcn_exp2f(sA[i]); sB[i] = __builtin_amdgcn_exp2f(sB[i]); la += sA[i]; lb_ += sB[i]; }
;                 lA += la; lB += lb_;
;                 u32x4 pwA[2], pwB[2];
; #pragma unroll
;                 for (int e = 0; e < 4; ++e) { pwA[0][e] = pk2(sA[2 * e], sA[2 * e + 1]); pwA[1][e] = pk2(sA[8 + 2 * e], sA[8 + 2 * e + 1]); pwB[0][e] = pk2(sB[2 * e], sB[2 * e + 1]); pwB[1][e] = pk2(sB[8 + 2 * e], sB[8 + 2 * e + 1]); }
; #pragma unroll
;                 for (int k2 = 0; k2 < 2; ++k2) { const int ks = 2 * half + k2;
;                     const u32x2 va0 = *(const LAS u32x2*)(vp + 16 * ks), va1 = *(const LAS u32x2*)(vp + 16 * ks + 8), vb0 = *(const LAS u32x2*)(vp + 32 * 68 + 16 * ks), vb1 = *(const LAS u32x2*)(vp + 32 * 68 + 16 * ks + 8);
;                     const bf16x8 v0 = __builtin_bit_cast(bf16x8, (u32x4){va0[0], va0[1], va1[0], va1[1]}), v1 = __builtin_bit_cast(bf16x8, (u32x4){vb0[0], vb0[1], vb1[0], vb1[1]});
;                     const bf16x8 pfA = __builtin_bit_cast(bf16x8, pwA[k2]), pfB = __builtin_bit_cast(bf16x8, pwB[k2]);
;                     oA0 = MFMA32(v0, pfA, oA0); oA1 = MFMA32(v1, pfA, oA1); oB0 = MFMA32(v0, pfB, oB0); oB1 = MFMA32(v1, pfB, oB1); }
;                 __builtin_amdgcn_sched_barrier(0);
;             }
;         }
;         if (t + 1 < NTL) ATT_STORE(buf ^ 1);
.LBB0_824:
	v_pk_add_f32 v[132:133], v[132:133], 0 op_sel_hi:[1,0]
	s_nop 7
	v_exp_f32_e32 v93, v93
	v_pk_add_f32 v[132:133], v[134:135], v[132:133]
	v_exp_f32_e32 v135, v81
	v_pk_add_f32 v[132:133], v[136:137], v[132:133]
	v_exp_f32_e32 v134, v97
	v_pk_add_f32 v[132:133], v[138:139], v[132:133]
	v_exp_f32_e32 v137, v82
	v_pk_add_f32 v[132:133], v[140:141], v[132:133]
	v_exp_f32_e32 v136, v98
	v_pk_add_f32 v[132:133], v[146:147], v[132:133]
	v_exp_f32_e32 v139, v83
	v_pk_add_f32 v[132:133], v[144:145], v[132:133]
	v_exp_f32_e32 v138, v99
	v_pk_add_f32 v[132:133], v[142:143], v[132:133]
	v_exp_f32_e32 v141, v84
	v_pk_add_f32 v[132:133], v[152:153], v[132:133]
	v_exp_f32_e32 v143, v85
	v_pk_add_f32 v[132:133], v[156:157], v[132:133]
	v_exp_f32_e32 v145, v86
	v_pk_add_f32 v[132:133], v[150:151], v[132:133]
	v_exp_f32_e32 v147, v87
	v_pk_add_f32 v[132:133], v[154:155], v[132:133]
	v_exp_f32_e32 v140, v100
	v_pk_add_f32 v[132:133], v[148:149], v[132:133]
	v_exp_f32_e32 v142, v101
	v_pk_add_f32 v[132:133], v[162:163], v[132:133]
	v_exp_f32_e32 v144, v102
	v_pk_add_f32 v[132:133], v[158:159], v[132:133]
	v_exp_f32_e32 v146, v103
	v_pk_add_f32 v[132:133], v[160:161], v[132:133]
	v_cvt_pk_bf16_f32 v85, v137, v139
	v_pk_add_f32 v[130:131], v[130:131], v[132:133]
	v_exp_f32_e32 v133, v80
	v_exp_f32_e32 v132, v96
	ds_read2_b64 v[80:83], v167 offset0:8 offset1:10
	ds_read2_b64 v[96:99], v168 offset0:40 offset1:42
	v_cvt_pk_bf16_f32 v84, v133, v135
	v_cvt_pk_bf16_f32 v86, v141, v143
	v_cvt_pk_bf16_f32 v87, v145, v147
	v_exp_f32_e32 v101, v88
	v_exp_f32_e32 v103, v89
	s_waitcnt lgkmcnt(1)
	v_mfma_f32_32x32x16_bf16 v[64:79], v[80:83], v[84:87], v[64:79]
	v_exp_f32_e32 v102, v105
	v_exp_f32_e32 v105, v90
	v_exp_f32_e32 v149, v91
	ds_read2_b64 v[88:91], v168 offset0:44 offset1:46
	v_exp_f32_e32 v148, v107
	v_exp_f32_e32 v107, v92
	v_exp_f32_e32 v92, v109
	s_waitcnt lgkmcnt(1)
	v_mfma_f32_32x32x16_bf16 v[48:63], v[96:99], v[84:87], v[48:63]
	v_cvt_pk_bf16_f32 v84, v132, v134
	v_cvt_pk_bf16_f32 v85, v136, v138
	v_cvt_pk_bf16_f32 v86, v140, v142
	v_cvt_pk_bf16_f32 v87, v144, v146
	v_exp_f32_e32 v109, v94
	v_exp_f32_e32 v95, v95
	v_exp_f32_e32 v100, v104
	v_mfma_f32_32x32x16_bf16 v[32:47], v[80:83], v[84:87], v[32:47]
	ds_read2_b64 v[80:83], v167 offset0:12 offset1:14
	v_exp_f32_e32 v104, v106
	v_exp_f32_e32 v106, v108
	v_exp_f32_e32 v108, v110
	v_exp_f32_e32 v94, v111
	v_mfma_f32_32x32x16_bf16 v[16:31], v[96:99], v[84:87], v[16:31]
	v_add_f32_e64 v96, v132, 0
	v_add_f32_e64 v97, v133, 0
	v_cvt_pk_bf16_f32 v84, v101, v103
	v_add_f32_e64 v96, v134, v96
	v_add_f32_e64 v97, v135, v97
	v_cvt_pk_bf16_f32 v85, v105, v149
	v_pk_add_f32 v[96:97], v[136:137], v[96:97]
	v_cvt_pk_bf16_f32 v86, v107, v93
	v_pk_add_f32 v[96:97], v[138:139], v[96:97]
	v_cvt_pk_bf16_f32 v87, v109, v95
	v_pk_add_f32 v[96:97], v[140:141], v[96:97]
	s_nop 0
	v_pk_add_f32 v[96:97], v[142:143], v[96:97]
	s_waitcnt lgkmcnt(0)
	v_mfma_f32_32x32x16_bf16 v[64:79], v[80:83], v[84:87], v[64:79]
	v_mfma_f32_32x32x16_bf16 v[48:63], v[88:91], v[84:87], v[48:63]
	v_add_f32_e64 v84, v144, v96
	v_add_f32_e64 v85, v145, v97
	v_cvt_pk_bf16_f32 v86, v106, v92
	v_add_f32_e64 v84, v146, v84
	v_add_f32_e64 v85, v147, v85
	v_cvt_pk_bf16_f32 v87, v108, v94
	v_pk_add_f32 v[96:97], v[100:101], v[84:85]
	v_cvt_pk_bf16_f32 v84, v100, v102
	v_cvt_pk_bf16_f32 v85, v104, v148
	s_nop 1
	v_mfma_f32_32x32x16_bf16 v[32:47], v[80:83], v[84:87], v[32:47]
	v_add_f32_e64 v80, v102, v96
	v_add_f32_e64 v81, v103, v97
	v_add_f32_e64 v80, v104, v80
	v_add_f32_e64 v81, v105, v81
	v_add_f32_e64 v80, v148, v80
	v_add_f32_e64 v81, v149, v81
	v_pk_add_f32 v[80:81], v[106:107], v[80:81]
	v_mfma_f32_32x32x16_bf16 v[16:31], v[88:91], v[84:87], v[16:31]
	v_add_f32_e64 v80, v92, v80
	v_add_f32_e64 v81, v93, v81
	v_add_f32_e64 v80, v108, v80
	v_add_f32_e64 v81, v109, v81
	v_add_f32_e64 v80, v94, v80
	v_add_f32_e64 v81, v95, v81
	v_pk_add_f32 v[130:131], v[130:131], v[80:81]
.Lattn_join_2:
	s_andn2_b64 vcc, exec, s[20:21]
	s_cbranch_vccnz .LBB0_828
.LBB0_825:
	s_xor_b32 s20, s29, 1
	s_mul_i32 s4, s20, 0x3400
	s_add_i32 s21, s4, 0
	v_add3_u32 v80, s21, v193, v192
	s_waitcnt vmcnt(1)
	ds_write_b128 v80, v[112:115]
	s_and_saveexec_b64 s[4:5], s[0:1]
	v_add3_u32 v80, s21, v191, v190
	ds_write_b128 v80, v[116:119]
	s_or_b64 exec, exec, s[4:5]
	s_mulk_i32 s20, 0x2200
	v_add_u32_e32 v80, s20, v189
	v_add_u32_e32 v80, 0x6800, v80
	s_waitcnt vmcnt(0)
	ds_write2_b64 v80, v[120:121], v[122:123] offset1:1

; #define LAS __attribute__((address_space(3)))
; __device__ __forceinline__ void attn_unit64(const bf16_t* Q, const bf16_t* K, const bf16_t* Vt, bf16_t* O, int bh, int qb8, float mfix, LAS unsigned char* lds) {
;     ...
;         if (t <= tmaxw) {
;             const LAS bf16_t* kp = Kb + buf * 6656 + r * 104 + 8 * hh;
;             const LAS bf16_t* vp = Vb + buf * 4352 + r * 68 + 4 * hh;
; #pragma unroll
;             for (int half = 0; half < 2; ++half) {
;                 f32x16 sA, sB;
; #pragma unroll
;                 for (int i = 0; i < 16; ++i) { sA[i] = -mfix; sB[i] = -mfix; }
; #pragma unroll
;                 for (int d0 = 0; d0 < 6; ++d0) { const bf16x8 a = *(const LAS bf16x8*)(kp + half * 32 * 104 + 16 * d0); const bf16x8 qa_ = Qs[512 * d0], qb_ = Qs[512 * (6 + d0)]; sA = MFMA32(a, qa_, sA); sB = MFMA32(a, qb_, sB); }
;                 if (t == tmaxw) {
;                     const int rowA = qw + r, rowB = qw + 32 + r;
; #pragma unroll
;                     for (int i = 0; i < 16; ++i) { const int kv = 64 * t + 32 * half + crow(i, hh); if (kv > rowA) sA[i] = -1e30f; if (kv > rowB) sB[i] = -1e30f; }
;                 }
;                 float la = 0.f, lb_ = 0.f;
; #pragma unroll
;                 for (int i = 0; i < 16; ++i) { sA[i] = __builtin_amdgcn_exp2f(sA[i]); sB[i] = __builtin_amdgcn_exp2f(sB[i]); la += sA[i]; lb_ += sB[i]; }
;                 lA += la; lB += lb_;
;                 u32x4 pwA[2], pwB[2];
; #pragma unroll
;                 for (int e = 0; e < 4; ++e) { pwA[0][e] = pk2(sA[2 * e], sA[2 * e + 1]); pwA[1][e] = pk2(sA[8 + 2 * e], sA[8 + 2 * e + 1]); pwB[0][e] = pk2(sB[2 * e], sB[2 * e + 1]); pwB[1][e] = pk2(sB[8 + 2 * e], sB[8 + 2 * e + 1]); }
; #pragma unroll
;                 for (int k2 = 0; k2 < 2; ++k2) { const int ks = 2 * half + k2;
;                     const u32x2 va0 = *(const LAS u32x2*)(vp + 16 * ks), va1 = *(const LAS u32x2*)(vp + 16 * ks + 8), vb0 = *(const LAS u32x2*)(vp + 32 * 68 + 16 * ks), vb1 = *(const LAS u32x2*)(vp + 32 * 68 + 16 * ks + 8);
;                     const bf16x8 v0 = __builtin_bit_cast(bf16x8, (u32x4){va0[0], va0[1], va1[0], va1[1]}), v1 = __builtin_bit_cast(bf16x8, (u32x4){vb0[0], vb0[1], vb1[0], vb1[1]});
;                     const bf16x8 pfA = __builtin_bit_cast(bf16x8, pwA[k2]), pfB = __builtin_bit_cast(bf16x8, pwB[k2]);
.Lattn_fast_2:
.Laq2_b1:
	s_mul_i32 s4, s29, 0x3400
	v_add_u32_e32 v180, s4, v188
	s_mul_i32 s4, s29, 0x2200
	v_add_u32_e32 v177, s4, v198
	v_add_u32_e32 v178, 0x6800, v177
	ds_read_b128 v[248:251], v180
	ds_read_b128 v[158:161], v180 offset:32
	s_setprio 1
	s_waitcnt lgkmcnt(1)
	v_mfma_f32_32x32x16_bf16 v[96:111], v[248:251], v[132:135], v[0:15]
	v_mfma_f32_32x32x16_bf16 v[80:95], v[248:251], v[214:217], v[0:15]
	ds_read_b128 v[248:251], v180 offset:64
	s_waitcnt lgkmcnt(1)
	v_mfma_f32_32x32x16_bf16 v[96:111], v[158:161], v[136:139], v[96:111]
	v_mfma_f32_32x32x16_bf16 v[80:95], v[158:161], v[218:221], v[80:95]
	ds_read_b128 v[158:161], v180 offset:96
	s_waitcnt lgkmcnt(1)
	v_mfma_f32_32x32x16_bf16 v[96:111], v[248:251], v[140:143], v[96:111]
	v_mfma_f32_32x32x16_bf16 v[80:95], v[248:251], v[232:235], v[80:95]
	ds_read_b128 v[248:251], v180 offset:128
	s_waitcnt lgkmcnt(1)
	v_mfma_f32_32x32x16_bf16 v[96:111], v[158:161], v[144:147], v[96:111]
	v_mfma_f32_32x32x16_bf16 v[80:95], v[158:161], v[236:239], v[80:95]
	ds_read_b128 v[158:161], v180 offset:160
	s_waitcnt lgkmcnt(1)
	v_mfma_f32_32x32x16_bf16 v[96:111], v[248:251], v[206:209], v[96:111]
	v_mfma_f32_32x32x16_bf16 v[80:95], v[248:251], v[240:243], v[80:95]
	s_waitcnt lgkmcnt(0)
	v_mfma_f32_32x32x16_bf16 v[96:111], v[158:161], v[210:213], v[96:111]
	v_mfma_f32_32x32x16_bf16 v[80:95], v[158:161], v[244:247], v[80:95]
	ds_read_b64 v[248:249], v178 offset:0
	ds_read_b64 v[250:251], v178 offset:16
	ds_read_b64 v[158:159], v178 offset:4352
	ds_read_b64 v[160:161], v178 offset:4368
	s_setprio 0
	s_nop 5
	v_exp_f32_e32 v96, v96
	v_exp_f32_e32 v97, v97
	v_exp_f32_e32 v98, v98
	v_exp_f32_e32 v99, v99
	v_add_f32_e32 v182, v96, v97
	v_cvt_pk_bf16_f32 v96, v96, v97
	v_exp_f32_e32 v100, v100
	v_exp_f32_e32 v101, v101
	v_add_f32_e32 v182, v182, v98
	v_add_f32_e32 v182, v182, v99
	v_cvt_pk_bf16_f32 v97, v98, v99
	v_exp_f32_e32 v102, v102
	v_exp_f32_e32 v103, v103
	v_add_f32_e32 v182, v182, v100
	v_add_f32_e32 v182, v182, v101
	v_cvt_pk_bf16_f32 v98, v100, v101
	v_exp_f32_e32 v80, v80
	v_exp_f32_e32 v81, v81
	v_add_f32_e32 v182, v182, v102
	v_add_f32_e32 v182, v182, v103
	v_cvt_pk_bf16_f32 v99, v102, v103
	v_exp_f32_e32 v82, v82
	v_exp_f32_e32 v83, v83
	v_add_f32_e32 v162, v80, v81
	v_cvt_pk_bf16_f32 v80, v80, v81
	v_exp_f32_e32 v84, v84
	v_exp_f32_e32 v85, v85
	v_add_f32_e32 v162, v162, v82
	v_add_f32_e32 v162, v162, v83
	v_cvt_pk_bf16_f32 v81, v82, v83
	v_exp_f32_e32 v86, v86
	v_exp_f32_e32 v87, v87
	v_add_f32_e32 v162, v162, v84
	v_add_f32_e32 v162, v162, v85
	v_cvt_pk_bf16_f32 v82, v84, v85
	v_exp_f32_e32 v104, v104
	v_exp_f32_e32 v105, v105
	v_add_f32_e32 v162, v162, v86
	v_add_f32_e32 v162, v162, v87
	v_cvt_pk_bf16_f32 v83, v86, v87
	v_exp_f32_e32 v106, v106
	v_exp_f32_e32 v107, v107
	v_add_f32_e32 v182, v182, v104
	v_add_f32_e32 v182, v182, v105
	v_cvt_pk_bf16_f32 v100, v104, v105
	v_exp_f32_e32 v108, v108
	v_exp_f32_e32 v109, v109
	v_add_f32_e32 v182, v182, v106
	v_add_f32_e32 v182, v182, v107
	v_cvt_pk_bf16_f32 v101, v106, v107
	v_exp_f32_e32 v110, v110
	v_exp_f32_e32 v111, v111
	v_add_f32_e32 v182, v182, v108
	v_add_f32_e32 v182, v182, v109
	v_cvt_pk_bf16_f32 v102, v108, v109
	v_exp_f32_e32 v88, v88
	v_exp_f32_e32 v89, v89
	v_add_f32_e32 v182, v182, v110
	v_add_f32_e32 v182, v182, v111
	v_cvt_pk_bf16_f32 v103, v110, v111
	ds_read_b64 v[104:105], v178 offset:32
	ds_read_b64 v[106:107], v178 offset:48
	ds_read_b64 v[108:109], v178 offset:4384
	ds_read_b64 v[110:111], v178 offset:4400
	v_exp_f32_e32 v90, v90
	v_exp_f32_e32 v91, v91
	v_add_f32_e32 v162, v162, v88
	v_add_f32_e32 v162, v162, v89
	v_cvt_pk_bf16_f32 v84, v88, v89
	v_exp_f32_e32 v92, v92
	v_exp_f32_e32 v93, v93
	v_add_f32_e32 v162, v162, v90
	v_add_f32_e32 v162, v162, v91
	v_cvt_pk_bf16_f32 v85, v90, v91
	v_exp_f32_e32 v94, v94
	v_exp_f32_e32 v95, v95
	v_add_f32_e32 v162, v162, v92
	v_add_f32_e32 v162, v162, v93
	v_cvt_pk_bf16_f32 v86, v92, v93
	v_add_f32_e32 v162, v162, v94
	v_add_f32_e32 v162, v162, v95
	v_cvt_pk_bf16_f32 v87, v94, v95
	v_add_f32_e32 v131, v131, v182
	v_add_f32_e32 v130, v130, v162
	s_setprio 1
	s_waitcnt lgkmcnt(6)
	v_mfma_f32_32x32x16_bf16 v[64:79], v[248:251], v[96:99], v[64:79]
	v_mfma_f32_32x32x16_bf16 v[32:47], v[248:251], v[80:83], v[32:47]
	s_waitcnt lgkmcnt(4)
	v_mfma_f32_32x32x16_bf16 v[48:63], v[158:161], v[96:99], v[48:63]
	v_mfma_f32_32x32x16_bf16 v[16:31], v[158:161], v[80:83], v[16:31]
	ds_read_b128 v[248:251], v180 offset:6656
	ds_read_b128 v[158:161], v180 offset:6688
	s_waitcnt lgkmcnt(4)
	v_mfma_f32_32x32x16_bf16 v[64:79], v[104:107], v[100:103], v[64:79]
	s_waitcnt lgkmcnt(2)
	v_mfma_f32_32x32x16_bf16 v[48:63], v[108:111], v[100:103], v[48:63]
	v_mfma_f32_32x32x16_bf16 v[32:47], v[104:107], v[84:87], v[32:47]
	v_mfma_f32_32x32x16_bf16 v[16:31], v[108:111], v[84:87], v[16:31]
	s_setprio 1
	s_waitcnt lgkmcnt(1)
	v_mfma_f32_32x32x16_bf16 v[96:111], v[248:251], v[132:135], v[0:15]
	v_mfma_f32_32x32x16_bf16 v[80:95], v[248:251], v[214:217], v[0:15]
	ds_read_b128 v[248:251], v180 offset:6720
	s_waitcnt lgkmcnt(1)
	v_mfma_f32_32x32x16_bf16 v[96:111], v[158:161], v[136:139], v[96:111]
	v_mfma_f32_32x32x16_bf16 v[80:95], v[158:161], v[218:221], v[80:95]
	ds_read_b128 v[158:161], v180 offset:6752
	s_waitcnt lgkmcnt(1)
	v_mfma_f32_32x32x16_bf16 v[96:111], v[248:251], v[140:143], v[96:111]
	v_mfma_f32_32x32x16_bf16 v[80:95], v[248:251], v[232:235], v[80:95]
	ds_read_b128 v[248:251], v180 offset:6784
	s_waitcnt lgkmcnt(1)
	v_mfma_f32_32x32x16_bf16 v[96:111], v[158:161], v[144:147], v[96:111]
	v_mfma_f32_32x32x16_bf16 v[80:95], v[158:161], v[236:239], v[80:95]
	ds_read_b128 v[158:161], v180 offset:6816
	s_waitcnt lgkmcnt(1)
; #define LAS __attribute__((address_space(3)))
; __device__ __forceinline__ unsigned pk2(float lo, float hi) { f32x2_t v = {lo, hi}; bf16x2_t b = __builtin_convertvector(v, bf16x2_t); return __builtin_bit_cast(unsigned, b); }
; #define MFMA32(a, b, c) __builtin_amdgcn_mfma_f32_32x32x16_bf16((a), (b), (c), 0, 0, 0)
; __device__ __forceinline__ void attn_unit64(const bf16_t* Q, const bf16_t* K, const bf16_t* Vt, bf16_t* O, int bh, int qb8, float mfix, LAS unsigned char* lds) {
;     ...
; #pragma unroll
;                 for (int i = 0; i < 16; ++i) { sA[i] = __builtin_amdgcn_exp2f(sA[i]); sB[i] = __builtin_amdgcn_exp2f(sB[i]); la += sA[i]; lb_ += sB[i]; }
;                 lA += la; lB += lb_;
;                 u32x4 pwA[2], pwB[2];
; #pragma unroll
;                 for (int e = 0; e < 4; ++e) { pwA[0][e] = pk2(sA[2 * e], sA[2 * e + 1]); pwA[1][e] = pk2(sA[8 + 2 * e], sA[8 + 2 * e + 1]); pwB[0][e] = pk2(sB[2 * e], sB[2 * e + 1]); pwB[1][e] = pk2(sB[8 + 2 * e], sB[8 + 2 * e + 1]); }
; #pragma unroll
;                 for (int k2 = 0; k2 < 2; ++k2) { const int ks = 2 * half + k2;
;                     const u32x2 va0 = *(const LAS u32x2*)(vp + 16 * ks), va1 = *(const LAS u32x2*)(vp + 16 * ks + 8), vb0 = *(const LAS u32x2*)(vp + 32 * 68 + 16 * ks), vb1 = *(const LAS u32x2*)(vp + 32 * 68 + 16 * ks + 8);
;                     const bf16x8 v0 = __builtin_bit_cast(bf16x8, (u32x4){va0[0], va0[1], va1[0], va1[1]}), v1 = __builtin_bit_cast(bf16x8, (u32x4){vb0[0], vb0[1], vb1[0], vb1[1]});
;                     const bf16x8 pfA = __builtin_bit_cast(bf16x8, pwA[k2]), pfB = __builtin_bit_cast(bf16x8, pwB[k2]);
;                     oA0 = MFMA32(v0, pfA, oA0); oA1 = MFMA32(v1, pfA, oA1); oB0 = MFMA32(v0, pfB, oB0); oB1 = MFMA32(v1, pfB, oB1); }
	v_mfma_f32_32x32x16_bf16 v[96:111], v[248:251], v[206:209], v[96:111]
	v_mfma_f32_32x32x16_bf16 v[80:95], v[248:251], v[240:243], v[80:95]
	s_waitcnt lgkmcnt(0)
	v_mfma_f32_32x32x16_bf16 v[96:111], v[158:161], v[210:213], v[96:111]
	v_mfma_f32_32x32x16_bf16 v[80:95], v[158:161], v[244:247], v[80:95]
	ds_read_b64 v[248:249], v178 offset:64
	ds_read_b64 v[250:251], v178 offset:80
	ds_read_b64 v[158:159], v178 offset:4416
	ds_read_b64 v[160:161], v178 offset:4432
	s_setprio 0
	s_nop 5
	v_exp_f32_e32 v96, v96
	v_exp_f32_e32 v97, v97
	v_exp_f32_e32 v98, v98
	v_exp_f32_e32 v99, v99
	v_add_f32_e32 v182, v96, v97
	v_cvt_pk_bf16_f32 v96, v96, v97
	v_exp_f32_e32 v100, v100
	v_exp_f32_e32 v101, v101
	v_add_f32_e32 v182, v182, v98
	v_add_f32_e32 v182, v182, v99
	v_cvt_pk_bf16_f32 v97, v98, v99
	v_exp_f32_e32 v102, v102
	v_exp_f32_e32 v103, v103
	v_add_f32_e32 v182, v182, v100
	v_add_f32_e32 v182, v182, v101
	v_cvt_pk_bf16_f32 v98, v100, v101
	v_exp_f32_e32 v80, v80
	v_exp_f32_e32 v81, v81
	v_add_f32_e32 v182, v182, v102
	v_add_f32_e32 v182, v182, v103
	v_cvt_pk_bf16_f32 v99, v102, v103
	v_exp_f32_e32 v82, v82
	v_exp_f32_e32 v83, v83
	v_add_f32_e32 v162, v80, v81
	v_cvt_pk_bf16_f32 v80, v80, v81
	v_exp_f32_e32 v84, v84
	v_exp_f32_e32 v85, v85
	v_add_f32_e32 v162, v162, v82
	v_add_f32_e32 v162, v162, v83
	v_cvt_pk_bf16_f32 v81, v82, v83
	v_exp_f32_e32 v86, v86
	v_exp_f32_e32 v87, v87
	v_add_f32_e32 v162, v162, v84
	v_add_f32_e32 v162, v162, v85
	v_cvt_pk_bf16_f32 v82, v84, v85
	v_exp_f32_e32 v104, v104
	v_exp_f32_e32 v105, v105
	v_add_f32_e32 v162, v162, v86
	v_add_f32_e32 v162, v162, v87
	v_cvt_pk_bf16_f32 v83, v86, v87
	v_exp_f32_e32 v106, v106
	v_exp_f32_e32 v107, v107
	v_add_f32_e32 v182, v182, v104
	v_add_f32_e32 v182, v182, v105
	v_cvt_pk_bf16_f32 v100, v104, v105
	v_exp_f32_e32 v108, v108
	v_exp_f32_e32 v109, v109
	v_add_f32_e32 v182, v182, v106
	v_add_f32_e32 v182, v182, v107
	v_cvt_pk_bf16_f32 v101, v106, v107
	v_exp_f32_e32 v110, v110
	v_exp_f32_e32 v111, v111
	v_add_f32_e32 v182, v182, v108
	v_add_f32_e32 v182, v182, v109
	v_cvt_pk_bf16_f32 v102, v108, v109
	v_exp_f32_e32 v88, v88
	v_exp_f32_e32 v89, v89
	v_add_f32_e32 v182, v182, v110
	v_add_f32_e32 v182, v182, v111
	v_cvt_pk_bf16_f32 v103, v110, v111
	ds_read_b64 v[104:105], v178 offset:96
	ds_read_b64 v[106:107], v178 offset:112
	ds_read_b64 v[108:109], v178 offset:4448
	ds_read_b64 v[110:111], v178 offset:4464
	v_exp_f32_e32 v90, v90
	v_exp_f32_e32 v91, v91
	v_add_f32_e32 v162, v162, v88
	v_add_f32_e32 v162, v162, v89
	v_cvt_pk_bf16_f32 v84, v88, v89
	v_exp_f32_e32 v92, v92
	v_exp_f32_e32 v93, v93
	v_add_f32_e32 v162, v162, v90
	v_add_f32_e32 v162, v162, v91
	v_cvt_pk_bf16_f32 v85, v90, v91
	v_exp_f32_e32 v94, v94
	v_exp_f32_e32 v95, v95
	v_add_f32_e32 v162, v162, v92
	v_add_f32_e32 v162, v162, v93
	v_cvt_pk_bf16_f32 v86, v92, v93
	v_add_f32_e32 v162, v162, v94
	v_add_f32_e32 v162, v162, v95
	v_cvt_pk_bf16_f32 v87, v94, v95
	v_add_f32_e32 v131, v131, v182
	v_add_f32_e32 v130, v130, v162
	s_setprio 1
	s_waitcnt lgkmcnt(6)
	v_mfma_f32_32x32x16_bf16 v[64:79], v[248:251], v[96:99], v[64:79]
	v_mfma_f32_32x32x16_bf16 v[32:47], v[248:251], v[80:83], v[32:47]
	s_waitcnt lgkmcnt(4)
	v_mfma_f32_32x32x16_bf16 v[48:63], v[158:161], v[96:99], v[48:63]
	v_mfma_f32_32x32x16_bf16 v[16:31], v[158:161], v[80:83], v[16:31]
	s_waitcnt lgkmcnt(2)
	v_mfma_f32_32x32x16_bf16 v[64:79], v[104:107], v[100:103], v[64:79]
	s_waitcnt lgkmcnt(0)
	v_mfma_f32_32x32x16_bf16 v[48:63], v[108:111], v[100:103], v[48:63]
	v_mfma_f32_32x32x16_bf16 v[32:47], v[104:107], v[84:87], v[32:47]
	v_mfma_f32_32x32x16_bf16 v[16:31], v[108:111], v[84:87], v[16:31]
	s_setprio 0
.Laq2_b5:
	s_branch .Lattn_join_2
; __device__ __forceinline__ void attn_unit64(const bf16_t* Q, const bf16_t* K, const bf16_t* Vt, bf16_t* O, int bh, int qb8, float mfix, LAS unsigned char* lds) {
;     ...
;     const float ltA = lA + __shfl_xor(lA, 32), ltB = lB + __shfl_xor(lB, 32), invA = 1.0f / ltA, invB = 1.0f / ltB;
;     const int b = bh >> 3, head = bh & 7;
;     ...
;     { bf16_t* rowA = O + (size_t)(b * SEQ + qw + r) * 1024 + head * 64; ATT_OSTORE(oA0, oA1, invA, rowA); ATT_OSTORE(oB0, oB1, invB, rowA + (size_t)32 * 1024); }
.LBB0_830:
	ds_bpermute_b32 v1, v187, v131
	v_add_u32_e32 v0, s3, v164
	v_mov_b32_e32 v129, 0
	ds_bpermute_b32 v14, v187, v130
	s_mov_b32 s3, 0x10000
	s_waitcnt lgkmcnt(1)
	v_add_f32_e32 v2, v131, v1
	v_div_scale_f32 v3, s[4:5], v2, v2, 1.0
	v_rcp_f32_e32 v4, v3
	v_div_scale_f32 v5, vcc, 1.0, v2, 1.0
	v_ashrrev_i32_e32 v1, 31, v0
	v_fma_f32 v6, -v3, v4, 1.0
	v_fmac_f32_e32 v4, v6, v4
	v_mul_f32_e32 v6, v5, v4
	v_fma_f32 v7, -v3, v6, v5
	v_fmac_f32_e32 v6, v7, v4
	v_fma_f32 v3, -v3, v6, v5
	v_div_fmas_f32 v3, v3, v4, v6
	v_lshlrev_b64 v[0:1], 11, v[0:1]
	v_div_fixup_f32 v4, v3, v2, 1.0
	v_lshl_add_u64 v[0:1], s[10:11], 0, v[0:1]
	v_lshl_add_u64 v[6:7], v[0:1], 0, v[128:129]
	v_pk_mul_f32 v[0:1], v[70:71], v[4:5] op_sel_hi:[1,0]
	v_pk_mul_f32 v[8:9], v[68:69], v[4:5] op_sel_hi:[1,0]
	v_pk_mul_f32 v[10:11], v[66:67], v[4:5] op_sel_hi:[1,0]
	v_pk_mul_f32 v[12:13], v[64:65], v[4:5] op_sel_hi:[1,0]
	v_cvt_pk_bf16_f32 v3, v0, v1
	v_cvt_pk_bf16_f32 v2, v8, v9
	v_cvt_pk_bf16_f32 v1, v10, v11
	v_cvt_pk_bf16_f32 v0, v12, v13
	s_nop 1
	v_permlane32_swap_b32_e32 v0, v2
	v_permlane32_swap_b32_e32 v1, v3
	global_store_dwordx4 v[6:7], v[0:3], off
	v_pk_mul_f32 v[8:9], v[76:77], v[4:5] op_sel_hi:[1,0]
	v_pk_mul_f32 v[10:11], v[74:75], v[4:5] op_sel_hi:[1,0]
	v_pk_mul_f32 v[0:1], v[78:79], v[4:5] op_sel_hi:[1,0]
	v_pk_mul_f32 v[12:13], v[72:73], v[4:5] op_sel_hi:[1,0]
	v_cvt_pk_bf16_f32 v3, v0, v1
	v_cvt_pk_bf16_f32 v2, v8, v9
	v_cvt_pk_bf16_f32 v1, v10, v11
	v_cvt_pk_bf16_f32 v0, v12, v13
	s_nop 1
	v_permlane32_swap_b32_e32 v0, v2
	v_permlane32_swap_b32_e32 v1, v3
	global_store_dwordx4 v[6:7], v[0:3], off offset:32
	v_pk_mul_f32 v[8:9], v[52:53], v[4:5] op_sel_hi:[1,0]
	v_pk_mul_f32 v[10:11], v[50:51], v[4:5] op_sel_hi:[1,0]
	v_pk_mul_f32 v[0:1], v[54:55], v[4:5] op_sel_hi:[1,0]
	v_pk_mul_f32 v[12:13], v[48:49], v[4:5] op_sel_hi:[1,0]
	v_cvt_pk_bf16_f32 v3, v0, v1
	v_cvt_pk_bf16_f32 v2, v8, v9
	v_cvt_pk_bf16_f32 v1, v10, v11
	v_cvt_pk_bf16_f32 v0, v12, v13
	s_nop 1
	v_permlane32_swap_b32_e32 v0, v2
	v_permlane32_swap_b32_e32 v1, v3
	global_store_dwordx4 v[6:7], v[0:3], off offset:64
	v_pk_mul_f32 v[8:9], v[60:61], v[4:5] op_sel_hi:[1,0]
	v_pk_mul_f32 v[10:11], v[58:59], v[4:5] op_sel_hi:[1,0]
	v_pk_mul_f32 v[0:1], v[62:63], v[4:5] op_sel_hi:[1,0]
	v_pk_mul_f32 v[4:5], v[56:57], v[4:5] op_sel_hi:[1,0]
	v_cvt_pk_bf16_f32 v3, v0, v1
	v_cvt_pk_bf16_f32 v0, v4, v5
	s_waitcnt lgkmcnt(0)
	v_add_f32_e32 v4, v130, v14
	v_div_scale_f32 v5, s[4:5], v4, v4, 1.0
	v_cvt_pk_bf16_f32 v2, v8, v9
	v_rcp_f32_e32 v8, v5
	v_cvt_pk_bf16_f32 v1, v10, v11
	v_permlane32_swap_b32_e32 v0, v2
	s_nop 0
	v_permlane32_swap_b32_e32 v1, v3
	global_store_dwordx4 v[6:7], v[0:3], off offset:96
	s_mov_b64 s[4:5], 0x10000
	s_nop 0
	v_fma_f32 v0, -v5, v8, 1.0
	v_fmac_f32_e32 v8, v0, v8
	v_div_scale_f32 v0, vcc, 1.0, v4, 1.0
	v_mul_f32_e32 v1, v0, v8
	v_fma_f32 v2, -v5, v1, v0
	v_fmac_f32_e32 v1, v2, v8
	v_fma_f32 v0, -v5, v1, v0
	v_div_fmas_f32 v0, v0, v8, v1
	v_div_fixup_f32 v4, v0, v4, 1.0
	v_pk_mul_f32 v[0:1], v[38:39], v[4:5] op_sel_hi:[1,0]
	v_pk_mul_f32 v[10:11], v[36:37], v[4:5] op_sel_hi:[1,0]
	v_pk_mul_f32 v[12:13], v[34:35], v[4:5] op_sel_hi:[1,0]
	v_pk_mul_f32 v[14:15], v[32:33], v[4:5] op_sel_hi:[1,0]
	v_lshl_add_u64 v[8:9], v[6:7], 0, s[4:5]
	v_cvt_pk_bf16_f32 v3, v0, v1
	v_cvt_pk_bf16_f32 v2, v10, v11
	v_cvt_pk_bf16_f32 v1, v12, v13
	v_cvt_pk_bf16_f32 v0, v14, v15
	v_add_co_u32_e32 v6, vcc, s3, v6
	s_nop 0
	v_permlane32_swap_b32_e32 v0, v2
	v_permlane32_swap_b32_e32 v1, v3
	v_addc_co_u32_e32 v7, vcc, 0, v7, vcc
	global_store_dwordx4 v[6:7], v[0:3], off
	v_pk_mul_f32 v[6:7], v[44:45], v[4:5] op_sel_hi:[1,0]
	v_pk_mul_f32 v[10:11], v[42:43], v[4:5] op_sel_hi:[1,0]
	v_pk_mul_f32 v[0:1], v[46:47], v[4:5] op_sel_hi:[1,0]
	v_pk_mul_f32 v[12:13], v[40:41], v[4:5] op_sel_hi:[1,0]
	v_cvt_pk_bf16_f32 v3, v0, v1
	v_cvt_pk_bf16_f32 v2, v6, v7
	v_cvt_pk_bf16_f32 v1, v10, v11
	v_cvt_pk_bf16_f32 v0, v12, v13
	s_nop 1
	v_permlane32_swap_b32_e32 v0, v2
	v_permlane32_swap_b32_e32 v1, v3
	global_store_dwordx4 v[8:9], v[0:3], off offset:32
	v_pk_mul_f32 v[6:7], v[20:21], v[4:5] op_sel_hi:[1,0]
	v_pk_mul_f32 v[10:11], v[18:19], v[4:5] op_sel_hi:[1,0]
	v_pk_mul_f32 v[0:1], v[22:23], v[4:5] op_sel_hi:[1,0]
	v_pk_mul_f32 v[12:13], v[16:17], v[4:5] op_sel_hi:[1,0]
	v_cvt_pk_bf16_f32 v3, v0, v1
	v_cvt_pk_bf16_f32 v2, v6, v7
	v_cvt_pk_bf16_f32 v1, v10, v11
	v_cvt_pk_bf16_f32 v0, v12, v13
	s_nop 1
	v_permlane32_swap_b32_e32 v0, v2
	v_permlane32_swap_b32_e32 v1, v3
	global_store_dwordx4 v[8:9], v[0:3], off offset:64
	v_pk_mul_f32 v[6:7], v[28:29], v[4:5] op_sel_hi:[1,0]
	v_pk_mul_f32 v[10:11], v[26:27], v[4:5] op_sel_hi:[1,0]
	v_pk_mul_f32 v[0:1], v[30:31], v[4:5] op_sel_hi:[1,0]
	v_pk_mul_f32 v[4:5], v[24:25], v[4:5] op_sel_hi:[1,0]
	v_cvt_pk_bf16_f32 v3, v0, v1
	v_cvt_pk_bf16_f32 v2, v6, v7
	v_cvt_pk_bf16_f32 v1, v10, v11
	v_cvt_pk_bf16_f32 v0, v4, v5
	s_nop 1
	v_permlane32_swap_b32_e32 v0, v2
	v_permlane32_swap_b32_e32 v1, v3
	s_mov_b64 s[4:5], -1
	global_store_dwordx4 v[8:9], v[0:3], off offset:96
